# GDN scan operands stored [h][kq] in LDS (conflict-free ds_read_b128) and gdn_prep conv-tap staging loads issued together instead of one round trip per pair
# speedup vs baseline: 1.0829x; 1.0065x over previous
; __device__ __forceinline__ void phase_gdn_prep(Ctx& C, int i) {
;     ...
;     for (int e = tid; e < 4 * GQKV; e += NTHR) cwl[e] = cw[e];
.LBB0_793:
	v_ashrrev_i32_e32 v11, 31, v0
	v_mov_b32_e32 v10, v0
	v_lshl_add_u64 v[10:11], v[10:11], 2, s[34:35]
	s_mov_b64 vcc, 0x1000
	global_load_dword v12, v[10:11], off
	global_load_dword v13, v[10:11], off offset:2048
	v_lshl_add_u64 v[10:11], v[10:11], 0, vcc
	global_load_dword v14, v[10:11], off
	global_load_dword v15, v[10:11], off offset:2048
	v_lshl_add_u64 v[10:11], v[10:11], 0, vcc
	global_load_dword v16, v[10:11], off
	global_load_dword v17, v[10:11], off offset:2048
	v_lshl_add_u64 v[10:11], v[10:11], 0, vcc
	global_load_dword v18, v[10:11], off
	global_load_dword v19, v[10:11], off offset:2048
	v_lshl_add_u64 v[10:11], v[10:11], 0, vcc
	global_load_dword v20, v[10:11], off
	global_load_dword v21, v[10:11], off offset:2048
	v_lshl_add_u64 v[10:11], v[10:11], 0, vcc
	global_load_dword v22, v[10:11], off
	global_load_dword v23, v[10:11], off offset:2048
	s_waitcnt vmcnt(0)
	ds_write2st64_b32 v6, v12, v13 offset1:8
	ds_write2st64_b32 v6, v14, v15 offset0:16 offset1:24
	ds_write2st64_b32 v6, v16, v17 offset0:32 offset1:40
	ds_write2st64_b32 v6, v18, v19 offset0:48 offset1:56
	ds_write2st64_b32 v6, v20, v21 offset0:64 offset1:72
	ds_write2st64_b32 v6, v22, v23 offset0:80 offset1:88

; #define LAS __attribute__((address_space(3)))
; __device__ __forceinline__ void bf8_to_lds(LAS float* dst, v4u c) {
;     *(LAS f32x4*)dst = (f32x4){bflo(c.x), bfhi(c.x), bflo(c.y), bfhi(c.y)};
;     *(LAS f32x4*)(dst + 4) = (f32x4){bflo(c.z), bfhi(c.z), bflo(c.w), bfhi(c.w)};
; }
.LBB0_928:
	s_and_b64 vcc, exec, s[38:39]
	s_cbranch_vccnz .LBB0_936
	v_lshlrev_b32_e32 v1, 5, v142
	v_and_b32_e32 v2, 1, v142
	v_bfe_u32 v28, v142, 1, 3
	v_lshlrev_b32_e32 v2, 8, v2
	v_lshl_or_b32 v2, v28, 4, v2
	v_and_b32_e32 v1, 0xe00, v1
	v_add3_u32 v1, 0, v2, v1
	s_waitcnt vmcnt(0)
	v_lshlrev_b32_e32 v28, 16, v12
	v_and_b32_e32 v29, 0xffff0000, v12
	v_lshlrev_b32_e32 v30, 16, v13
	v_and_b32_e32 v31, 0xffff0000, v13
	ds_write_b128 v1, v[28:31] offset:43264
	v_lshlrev_b32_e32 v28, 16, v14
	v_and_b32_e32 v29, 0xffff0000, v14
	v_lshlrev_b32_e32 v30, 16, v15
	v_and_b32_e32 v31, 0xffff0000, v15
	ds_write_b128 v1, v[28:31] offset:43392
	v_lshlrev_b32_e32 v28, 16, v16
	v_and_b32_e32 v29, 0xffff0000, v16
	v_lshlrev_b32_e32 v30, 16, v17
	v_and_b32_e32 v31, 0xffff0000, v17
	ds_write_b128 v1, v[28:31] offset:47360
	v_lshlrev_b32_e32 v28, 16, v18
	v_and_b32_e32 v29, 0xffff0000, v18
	v_lshlrev_b32_e32 v30, 16, v19
	v_and_b32_e32 v31, 0xffff0000, v19
	ds_write_b128 v1, v[28:31] offset:47488
	v_lshlrev_b32_e32 v28, 16, v8
	v_and_b32_e32 v29, 0xffff0000, v8
	v_lshlrev_b32_e32 v30, 16, v9
	v_and_b32_e32 v31, 0xffff0000, v9
	ds_write_b128 v1, v[28:31] offset:51456
	v_lshlrev_b32_e32 v28, 16, v10
	v_and_b32_e32 v29, 0xffff0000, v10
	v_lshlrev_b32_e32 v30, 16, v11
	v_and_b32_e32 v31, 0xffff0000, v11
	v_and_b32_e32 v0, 0x7f, v142
	ds_write_b128 v1, v[28:31] offset:51584
	v_lshlrev_b32_e32 v28, 16, v4
	v_and_b32_e32 v29, 0xffff0000, v4
	v_lshlrev_b32_e32 v30, 16, v5
	v_and_b32_e32 v31, 0xffff0000, v5
	ds_write_b128 v1, v[28:31] offset:55552
	v_lshlrev_b32_e32 v28, 16, v6
	v_and_b32_e32 v29, 0xffff0000, v6
	v_lshlrev_b32_e32 v30, 16, v7
	v_and_b32_e32 v31, 0xffff0000, v7
	v_cmp_lt_u32_e32 vcc, 31, v0
	ds_write_b128 v1, v[28:31] offset:55680
	s_and_saveexec_b64 s[0:1], vcc
	s_xor_b64 s[0:1], exec, s[0:1]
	s_cbranch_execz .LBB0_933
	v_cmp_gt_u32_e32 vcc, 48, v0
	s_and_saveexec_b64 s[4:5], vcc
	v_lshl_add_u32 v0, v0, 4, 0
	ds_write_b128 v0, v[20:23] offset:60160
	s_or_b64 exec, exec, s[4:5]

; #define LAS __attribute__((address_space(3)))
; __device__ __forceinline__ void phase_scan(Ctx& C, int i) {
;     ...
;             G_DESC(blk, m0, tb, head, cgp, b, isprompt)
;             const bool last = isprompt ? (blk == 127) : true;
;             if (blk + 1 < SC_NBLK) G_STAGE_LOAD(blk + 1);
;             const LAS float* B = buf0 + (blk & 1) * GBUF;
;             const int col = cgp * 16 + w * 8 + sub;
;             float* oo = ORAW + m0 * GW + head * 128 + col;
;             if (cw) {
;             if (tb == 16) gdn_block8<16>(S, B, kq, w * 8 + sub, oo); else gdn_block8<8>(S, B, kq, w * 8 + sub, oo);
.LBB0_966:
	s_andn2_b64 vcc, exec, s[42:43]
	s_cbranch_vccnz .LBB0_972
	s_lshl_b32 s4, s62, 4
	s_and_b32 s4, s4, 0x70
	s_or_b32 s4, s59, s4
	v_or_b32_e32 v0, s4, v161
	s_lshl_b64 s[4:5], s[40:41], 11
	v_readlane_b32 s40, v251, 60
	s_add_u32 s40, s40, s4
	v_readlane_b32 s4, v251, 61
	s_addc_u32 s41, s4, s5
	s_lshl_b32 s84, s61, 7
	s_lshl_b64 s[4:5], s[84:85], 2
	s_add_u32 s4, s40, s4
	s_addc_u32 s5, s41, s5
	s_bitcmp1_b32 s2, 0
	s_cselect_b32 s2, 0x1140, 0
	v_lshlrev_b32_e32 v2, 2, v0
	s_lshl_b32 s49, s2, 2
	v_lshl_add_u64 v[0:1], s[4:5], 0, v[2:3]
	s_add_i32 s2, s49, 0
	s_lshl_b32 s4, s59, 2
	v_lshlrev_b32_e32 v162, 4, v156
	s_add_i32 s4, s2, s4
	v_add_u32_e32 v157, s2, v162
	v_lshl_add_u32 v158, v161, 2, s4
	v_add_u32_e32 v159, 0xa900, v157
	v_add_u32_e32 v160, 0xa900, v158
	s_add_i32 s48, s2, 0xed00
	s_mov_b64 s[4:5], -1
	s_and_b64 vcc, exec, s[34:35]
	s_cbranch_vccnz .LBB0_980
	s_and_b64 vcc, exec, s[4:5]
	s_cbranch_vccnz .LBB0_983

; #define LAS __attribute__((address_space(3)))
; __device__ __forceinline__ void bf8_to_lds(LAS float* dst, v4u c) {
;     *(LAS f32x4*)dst = (f32x4){bflo(c.x), bfhi(c.x), bflo(c.y), bfhi(c.y)};
;     *(LAS f32x4*)(dst + 4) = (f32x4){bflo(c.z), bfhi(c.z), bflo(c.w), bfhi(c.w)};
; }
.LBB0_972:
	s_andn2_b64 vcc, exec, s[44:45]
	s_cbranch_vccnz .LBB0_938
	s_and_b64 vcc, exec, s[38:39]
	s_cbranch_vccnz .LBB0_938
	s_bitcmp1_b32 s29, 0
	s_cselect_b32 s0, 0x4500, 0
	v_lshlrev_b32_e32 v1, 5, v138
	s_add_i32 s2, s0, 0
	v_and_b32_e32 v2, 1, v138
	v_bfe_u32 v28, v138, 1, 3
	v_lshlrev_b32_e32 v2, 8, v2
	v_lshl_or_b32 v2, v28, 4, v2
	v_and_b32_e32 v1, 0xe00, v1
	v_add3_u32 v1, s2, v2, v1
	s_waitcnt vmcnt(1)
	v_lshlrev_b32_e32 v28, 16, v12
	v_and_b32_e32 v29, 0xffff0000, v12
	v_lshlrev_b32_e32 v30, 16, v13
	v_and_b32_e32 v31, 0xffff0000, v13
	ds_write_b128 v1, v[28:31] offset:43264
	v_lshlrev_b32_e32 v28, 16, v14
	v_and_b32_e32 v29, 0xffff0000, v14
	v_lshlrev_b32_e32 v30, 16, v15
	v_and_b32_e32 v31, 0xffff0000, v15
	ds_write_b128 v1, v[28:31] offset:43392
	s_waitcnt vmcnt(0)
	v_lshlrev_b32_e32 v28, 16, v16
	v_and_b32_e32 v29, 0xffff0000, v16
	v_lshlrev_b32_e32 v30, 16, v17
	v_and_b32_e32 v31, 0xffff0000, v17
	ds_write_b128 v1, v[28:31] offset:47360
	v_lshlrev_b32_e32 v28, 16, v18
	v_and_b32_e32 v29, 0xffff0000, v18
	v_lshlrev_b32_e32 v30, 16, v19
	v_and_b32_e32 v31, 0xffff0000, v19
	ds_write_b128 v1, v[28:31] offset:47488
	v_lshlrev_b32_e32 v28, 16, v8
	v_and_b32_e32 v29, 0xffff0000, v8
	v_lshlrev_b32_e32 v30, 16, v9
	v_and_b32_e32 v31, 0xffff0000, v9
	ds_write_b128 v1, v[28:31] offset:51456
	v_lshlrev_b32_e32 v28, 16, v10
	v_and_b32_e32 v29, 0xffff0000, v10
	v_lshlrev_b32_e32 v30, 16, v11
	v_and_b32_e32 v31, 0xffff0000, v11
	v_and_b32_e32 v0, 0x7f, v138
	ds_write_b128 v1, v[28:31] offset:51584
	v_lshlrev_b32_e32 v28, 16, v4
	v_and_b32_e32 v29, 0xffff0000, v4
	v_lshlrev_b32_e32 v30, 16, v5
	v_and_b32_e32 v31, 0xffff0000, v5
	ds_write_b128 v1, v[28:31] offset:55552
	v_lshlrev_b32_e32 v28, 16, v6
	v_and_b32_e32 v29, 0xffff0000, v6
	v_lshlrev_b32_e32 v30, 16, v7
	v_and_b32_e32 v31, 0xffff0000, v7
	v_cmp_lt_u32_e32 vcc, 31, v0
	ds_write_b128 v1, v[28:31] offset:55680
	s_and_saveexec_b64 s[0:1], vcc
	s_xor_b64 s[0:1], exec, s[0:1]
	s_cbranch_execz .LBB0_978
	v_cmp_gt_u32_e32 vcc, 48, v0
	s_and_saveexec_b64 s[4:5], vcc
	v_lshl_add_u32 v0, v0, 4, s2
	ds_write_b128 v0, v[20:23] offset:60160
	s_or_b64 exec, exec, s[4:5]

; #define LAS __attribute__((address_space(3)))
; __device__ __forceinline__ f32x2 fma2(f32x2 a, f32x2 b, f32x2 c) { return __builtin_elementwise_fma(a, b, c); }
; __device__ __forceinline__ float sum8(float x) { x += dppf<0x141>(x); x += dppf<0x4E>(x); x += dppf<0xB1>(x); return x; }
; __device__ __forceinline__ GOps8 g_ld8(const LAS float* B, int t, int kq, int vidx) {
;     GOps8 o; const LAS float* V = B + t * 256 + kq * 16;
; #pragma unroll
;     for (int h = 0; h < 4; ++h) { o.q[h] = *(const LAS f32x4*)(V + 4 * h); o.k[h] = *(const LAS f32x4*)(V + 128 + 4 * h); }
;     o.v = B[4096 + t * 16 + vidx]; o.sc = *(const LAS f32x4*)(B + 4352 + t * 4); return o;
; template <int TB> __device__ __forceinline__ void gdn_block8(f32x2 (&S)[8], const LAS float* B, int kq, int vidx, float* oo) {
;     float okA = 0.f, okB = 0.f;
;     GOps8 c = g_ld8(B, 0, kq, vidx);
; #pragma unroll 1
;     for (int t0 = 0; t0 < TB; t0 += SCAN_UNR) {
;         float P = 1.f, iP = 1.f;
; #pragma unroll
;         for (int tt = 0; tt < SCAN_UNR; ++tt) {
;             const int t = t0 + tt;
;             const GOps8 n = g_ld8(B, (t + 1) & 15, kq, vidx);
;             const f32x2 k[8] = PAIRS8(c.k), q[8] = PAIRS8(c.q);
;             f32x2 pk = S[0] * k[0], pq = S[0] * q[0];
; #pragma unroll
;             for (int e = 1; e < 8; ++e) { pk = fma2(S[e], k[e], pk); pq = fma2(S[e], q[e], pq); }
;             const float dk = sum8(pk.x + pk.y), dq = sum8(pq.x + pq.y);
;             P *= c.sc.x; iP *= c.sc.w;
;             const float coef = c.sc.y * (c.v - P * dk);
;             const float cs = coef * iP; const f32x2 cf2 = {cs, cs};
; #pragma unroll
;             for (int e = 0; e < 8; ++e) S[e] = fma2(k[e], cf2, S[e]);
;             const float o = P * dq + c.sc.z * coef;
;             okA = (kq == t) ? o : okA; okB = (kq + 8 == t) ? o : okB;
;             c = n;
;         }
.LBB0_981:
	ds_read_b128 v[48:51], v47
	ds_read_b128 v[52:55], v47 offset:128
	ds_read_b128 v[56:59], v47 offset:256
	ds_read_b128 v[68:71], v47 offset:384
	ds_read_b128 v[104:107], v47 offset:512
	ds_read_b128 v[124:127], v47 offset:640
	ds_read_b128 v[128:131], v47 offset:768
	ds_read_b128 v[132:135], v47 offset:896
	ds_read_b32 v45, v46 offset:16384
	v_mov_b32_e32 v46, s5
	s_or_b32 s34, s4, 1
	ds_read_b128 v[60:63], v46
	v_lshl_add_u32 v46, s34, 10, v157
	s_lshl_b32 s5, s34, 4
	ds_read_b128 v[100:103], v46 offset:43264
	ds_read_b128 v[96:99], v46 offset:43392
	ds_read_b128 v[92:95], v46 offset:43520
	ds_read_b128 v[88:91], v46 offset:43648
	ds_read_b128 v[80:83], v46 offset:43776
	ds_read_b128 v[76:79], v46 offset:43904
	ds_read_b128 v[72:75], v46 offset:44032
	ds_read_b128 v[64:67], v46 offset:44160
	v_lshl_add_u32 v46, s34, 6, v158
	s_add_i32 s5, s2, s5
	ds_read_b32 v163, v46 offset:59648
	v_mov_b32_e32 v46, s5
	ds_read_b128 v[84:87], v46 offset:60672
	s_waitcnt lgkmcnt(14)
	v_pk_mul_f32 v[46:47], v[42:43], v[104:105]
	v_pk_mul_f32 v[48:49], v[42:43], v[48:49]
	v_pk_fma_f32 v[46:47], v[40:41], v[106:107], v[46:47]
	v_pk_fma_f32 v[48:49], v[40:41], v[50:51], v[48:49]
	v_pk_fma_f32 v[46:47], v[38:39], v[124:125], v[46:47]
	v_pk_fma_f32 v[48:49], v[38:39], v[52:53], v[48:49]
	v_pk_fma_f32 v[46:47], v[36:37], v[126:127], v[46:47]
	v_pk_fma_f32 v[48:49], v[36:37], v[54:55], v[48:49]
	s_waitcnt lgkmcnt(13)
	v_pk_fma_f32 v[46:47], v[34:35], v[128:129], v[46:47]
	v_pk_fma_f32 v[48:49], v[34:35], v[56:57], v[48:49]
	v_pk_fma_f32 v[46:47], v[32:33], v[130:131], v[46:47]
	v_pk_fma_f32 v[48:49], v[32:33], v[58:59], v[48:49]
	s_waitcnt lgkmcnt(12)
	v_pk_fma_f32 v[46:47], v[30:31], v[132:133], v[46:47]
	v_pk_fma_f32 v[48:49], v[30:31], v[68:69], v[48:49]
	v_pk_fma_f32 v[46:47], v[28:29], v[134:135], v[46:47]
	v_pk_fma_f32 v[48:49], v[28:29], v[70:71], v[48:49]
	v_add_f32_e32 v46, v46, v47
	v_add_f32_e32 v47, v48, v49
	s_or_b32 s5, s4, 2
	v_add_f32_dpp v46, v46, v46 row_half_mirror row_mask:0xf bank_mask:0xf bound_ctrl:1
	v_add_f32_dpp v47, v47, v47 row_half_mirror row_mask:0xf bank_mask:0xf bound_ctrl:1
	v_cmp_eq_u32_e32 vcc, s4, v156
	v_add_f32_dpp v46, v46, v46 quad_perm:[2,3,0,1] row_mask:0xf bank_mask:0xf bound_ctrl:1
	v_add_f32_dpp v48, v47, v47 quad_perm:[2,3,0,1] row_mask:0xf bank_mask:0xf bound_ctrl:1
	s_lshl_b32 s35, s5, 4
	v_add_f32_dpp v46, v46, v46 quad_perm:[1,0,3,2] row_mask:0xf bank_mask:0xf bound_ctrl:1
	s_waitcnt lgkmcnt(10)
	v_fma_f32 v47, -v60, v46, v45
	s_add_i32 s35, s2, s35
	v_add_f32_dpp v46, v48, v48 quad_perm:[1,0,3,2] row_mask:0xf bank_mask:0xf bound_ctrl:1
	v_pk_mul_f32 v[46:47], v[60:61], v[46:47]
	s_nop 0
	v_mul_f32_e32 v48, v63, v47
	v_pk_fma_f32 v[104:105], v[104:105], v[48:49], v[42:43] op_sel_hi:[1,0,1]
	v_pk_fma_f32 v[106:107], v[106:107], v[48:49], v[40:41] op_sel_hi:[1,0,1]
	v_pk_fma_f32 v[136:137], v[134:135], v[48:49], v[28:29] op_sel_hi:[1,0,1]
	s_waitcnt lgkmcnt(5)
	v_pk_mul_f32 v[134:135], v[80:81], v[104:105]
	v_pk_fma_f32 v[124:125], v[124:125], v[48:49], v[38:39] op_sel_hi:[1,0,1]
	v_pk_mul_f32 v[100:101], v[100:101], v[104:105]
	v_pk_fma_f32 v[134:135], v[106:107], v[82:83], v[134:135]
	v_pk_fma_f32 v[126:127], v[126:127], v[48:49], v[36:37] op_sel_hi:[1,0,1]
	v_pk_fma_f32 v[100:101], v[106:107], v[102:103], v[100:101]
	s_waitcnt lgkmcnt(4)
	v_pk_fma_f32 v[102:103], v[124:125], v[76:77], v[134:135]
	v_pk_fma_f32 v[128:129], v[128:129], v[48:49], v[34:35] op_sel_hi:[1,0,1]
	v_pk_fma_f32 v[96:97], v[124:125], v[96:97], v[100:101]
	v_pk_fma_f32 v[100:101], v[126:127], v[78:79], v[102:103]
	v_pk_fma_f32 v[130:131], v[130:131], v[48:49], v[32:33] op_sel_hi:[1,0,1]
	v_pk_fma_f32 v[96:97], v[126:127], v[98:99], v[96:97]
	s_waitcnt lgkmcnt(3)
	v_pk_fma_f32 v[98:99], v[128:129], v[72:73], v[100:101]
	v_pk_fma_f32 v[132:133], v[132:133], v[48:49], v[30:31] op_sel_hi:[1,0,1]
	v_pk_fma_f32 v[92:93], v[128:129], v[92:93], v[96:97]
	v_pk_fma_f32 v[96:97], v[130:131], v[74:75], v[98:99]
	v_pk_fma_f32 v[92:93], v[130:131], v[94:95], v[92:93]
	s_waitcnt lgkmcnt(2)
	v_pk_fma_f32 v[94:95], v[132:133], v[64:65], v[96:97]
	v_pk_fma_f32 v[88:89], v[132:133], v[88:89], v[92:93]
	v_pk_fma_f32 v[92:93], v[136:137], v[66:67], v[94:95]
	s_waitcnt lgkmcnt(0)
	v_mul_f32_e32 v100, v60, v84
	v_add_f32_e32 v61, v92, v93
	v_mov_b32_e32 v84, v87
	v_mov_b32_e32 v60, v63
	v_add_f32_dpp v61, v61, v61 row_half_mirror row_mask:0xf bank_mask:0xf bound_ctrl:1
	v_lshl_add_u32 v28, s5, 10, v157
	ds_read_b128 v[68:71], v28 offset:43264
	ds_read_b128 v[56:59], v28 offset:43392
	ds_read_b128 v[52:55], v28 offset:43520
	ds_read_b128 v[48:51], v28 offset:43648
	ds_read_b128 v[40:43], v28 offset:43776
	ds_read_b128 v[36:39], v28 offset:43904
	ds_read_b128 v[32:35], v28 offset:44032
	ds_read_b128 v[28:31], v28 offset:44160
	v_add_f32_dpp v61, v61, v61 quad_perm:[2,3,0,1] row_mask:0xf bank_mask:0xf bound_ctrl:1
	v_pk_fma_f32 v[88:89], v[136:137], v[90:91], v[88:89]
	v_fmac_f32_e32 v46, v62, v47
	v_add_f32_dpp v61, v61, v61 quad_perm:[1,0,3,2] row_mask:0xf bank_mask:0xf bound_ctrl:1
	v_fma_f32 v61, -v100, v61, v163
	v_pk_mul_f32 v[134:135], v[84:85], v[60:61]
	v_cndmask_b32_e32 v167, v44, v46, vcc
	v_pk_mul_f32 v[60:61], v[134:135], v[134:135] op_sel:[0,1] op_sel_hi:[0,1]
	v_pk_fma_f32 v[102:103], v[80:81], v[60:61], v[104:105]
	v_pk_fma_f32 v[104:105], v[82:83], v[60:61], v[106:107]
	v_pk_fma_f32 v[106:107], v[76:77], v[60:61], v[124:125]
	v_pk_fma_f32 v[124:125], v[78:79], v[60:61], v[126:127]
	v_pk_fma_f32 v[126:127], v[72:73], v[60:61], v[128:129]
	v_pk_fma_f32 v[128:129], v[74:75], v[60:61], v[130:131]
	v_pk_fma_f32 v[130:131], v[64:65], v[60:61], v[132:133]
	v_pk_fma_f32 v[132:133], v[66:67], v[60:61], v[136:137]
	s_waitcnt lgkmcnt(3)
; __device__ __forceinline__ f32x2 fma2(f32x2 a, f32x2 b, f32x2 c) { return __builtin_elementwise_fma(a, b, c); }
; __device__ __forceinline__ float sum8(float x) { x += dppf<0x141>(x); x += dppf<0x4E>(x); x += dppf<0xB1>(x); return x; }
; template <int TB> __device__ __forceinline__ void gdn_block8(f32x2 (&S)[8], const LAS float* B, int kq, int vidx, float* oo) {
;     ...
;     for (int t0 = 0; t0 < TB; t0 += SCAN_UNR) {
;         float P = 1.f, iP = 1.f;
; #pragma unroll
;         for (int tt = 0; tt < SCAN_UNR; ++tt) {
;             const int t = t0 + tt;
;             const GOps8 n = g_ld8(B, (t + 1) & 15, kq, vidx);
;             const f32x2 k[8] = PAIRS8(c.k), q[8] = PAIRS8(c.q);
;             f32x2 pk = S[0] * k[0], pq = S[0] * q[0];
; #pragma unroll
;             for (int e = 1; e < 8; ++e) { pk = fma2(S[e], k[e], pk); pq = fma2(S[e], q[e], pq); }
;             const float dk = sum8(pk.x + pk.y), dq = sum8(pq.x + pq.y);
;             P *= c.sc.x; iP *= c.sc.w;
;             const float coef = c.sc.y * (c.v - P * dk);
;             const float cs = coef * iP; const f32x2 cf2 = {cs, cs};
; #pragma unroll
;             for (int e = 0; e < 8; ++e) S[e] = fma2(k[e], cf2, S[e]);
;             const float o = P * dq + c.sc.z * coef;
;             okA = (kq == t) ? o : okA; okB = (kq + 8 == t) ? o : okB;
;             c = n;
;         }
;         const f32x2 p2 = {P, P};
; #pragma unroll
;         for (int e = 0; e < 8; ++e) S[e] = S[e] * p2;
;     }
;     oo[(size_t)kq * GW] = okA;
;     if (TB == 16) oo[(size_t)(kq + 8) * GW] = okB;
	v_pk_mul_f32 v[136:137], v[40:41], v[102:103]
	v_pk_mul_f32 v[68:69], v[68:69], v[102:103]
	v_pk_fma_f32 v[136:137], v[104:105], v[42:43], v[136:137]
	v_pk_fma_f32 v[68:69], v[104:105], v[70:71], v[68:69]
	s_waitcnt lgkmcnt(2)
	v_pk_fma_f32 v[70:71], v[106:107], v[36:37], v[136:137]
	v_pk_fma_f32 v[56:57], v[106:107], v[56:57], v[68:69]
	v_pk_fma_f32 v[68:69], v[124:125], v[38:39], v[70:71]
	v_lshl_add_u32 v44, s5, 6, v158
	v_pk_fma_f32 v[56:57], v[124:125], v[58:59], v[56:57]
	s_waitcnt lgkmcnt(1)
	v_pk_fma_f32 v[58:59], v[126:127], v[32:33], v[68:69]
	ds_read_b32 v168, v44 offset:59648
	v_mov_b32_e32 v44, s35
	v_pk_fma_f32 v[52:53], v[126:127], v[52:53], v[56:57]
	v_pk_fma_f32 v[56:57], v[128:129], v[34:35], v[58:59]
	ds_read_b128 v[44:47], v44 offset:60672
	v_pk_fma_f32 v[52:53], v[128:129], v[54:55], v[52:53]
	s_waitcnt lgkmcnt(2)
	v_pk_fma_f32 v[54:55], v[130:131], v[28:29], v[56:57]
	v_add_f32_e32 v62, v88, v89
	v_pk_fma_f32 v[48:49], v[130:131], v[48:49], v[52:53]
	v_pk_fma_f32 v[52:53], v[132:133], v[30:31], v[54:55]
	v_add_f32_dpp v62, v62, v62 row_half_mirror row_mask:0xf bank_mask:0xf bound_ctrl:1
	v_pk_fma_f32 v[48:49], v[132:133], v[50:51], v[48:49]
	v_add_f32_e32 v50, v52, v53
	v_add_f32_dpp v62, v62, v62 quad_perm:[2,3,0,1] row_mask:0xf bank_mask:0xf bound_ctrl:1
	v_mov_b32_e32 v63, v86
	v_add_f32_dpp v50, v50, v50 row_half_mirror row_mask:0xf bank_mask:0xf bound_ctrl:1
	v_add_f32_dpp v62, v62, v62 quad_perm:[1,0,3,2] row_mask:0xf bank_mask:0xf bound_ctrl:1
	v_mov_b32_e32 v101, v135
	v_add_f32_dpp v50, v50, v50 quad_perm:[2,3,0,1] row_mask:0xf bank_mask:0xf bound_ctrl:1
	v_pk_mul_f32 v[60:61], v[62:63], v[100:101]
	s_waitcnt lgkmcnt(0)
	v_mul_f32_e32 v52, v100, v44
	v_add_f32_dpp v50, v50, v50 quad_perm:[1,0,3,2] row_mask:0xf bank_mask:0xf bound_ctrl:1
	v_add_f32_e32 v60, v60, v61
	v_cmp_eq_u32_e32 vcc, s34, v156
	s_or_b32 s34, s4, 3
	v_add_f32_e32 v48, v48, v49
	v_fma_f32 v135, -v52, v50, v168
	v_mov_b32_e32 v44, v47
	v_cndmask_b32_e32 v101, v167, v60, vcc
	v_lshl_add_u32 v60, s34, 10, v157
	v_add_f32_dpp v48, v48, v48 row_half_mirror row_mask:0xf bank_mask:0xf bound_ctrl:1
	v_pk_mul_f32 v[44:45], v[134:135], v[44:45]
	ds_read_b128 v[96:99], v60 offset:43264
	ds_read_b128 v[92:95], v60 offset:43392
	ds_read_b128 v[88:91], v60 offset:43520
	ds_read_b128 v[84:87], v60 offset:43648
	ds_read_b128 v[76:79], v60 offset:43776
	ds_read_b128 v[72:75], v60 offset:43904
	ds_read_b128 v[64:67], v60 offset:44032
	ds_read_b128 v[60:63], v60 offset:44160
	v_add_f32_dpp v51, v48, v48 quad_perm:[2,3,0,1] row_mask:0xf bank_mask:0xf bound_ctrl:1
	v_pk_mul_f32 v[48:49], v[44:45], v[44:45] op_sel:[0,1] op_sel_hi:[0,1]
	v_pk_fma_f32 v[40:41], v[40:41], v[48:49], v[102:103]
	v_pk_fma_f32 v[42:43], v[42:43], v[48:49], v[104:105]
	v_pk_fma_f32 v[36:37], v[36:37], v[48:49], v[106:107]
	v_pk_fma_f32 v[38:39], v[38:39], v[48:49], v[124:125]
	v_pk_fma_f32 v[32:33], v[32:33], v[48:49], v[126:127]
	v_pk_fma_f32 v[34:35], v[34:35], v[48:49], v[128:129]
	v_pk_fma_f32 v[28:29], v[28:29], v[48:49], v[130:131]
	v_pk_fma_f32 v[30:31], v[30:31], v[48:49], v[132:133]
	s_waitcnt lgkmcnt(3)
	v_pk_mul_f32 v[48:49], v[76:77], v[40:41]
	v_add_f32_dpp v47, v51, v51 quad_perm:[1,0,3,2] row_mask:0xf bank_mask:0xf bound_ctrl:1
	v_pk_mul_f32 v[50:51], v[96:97], v[40:41]
	v_pk_fma_f32 v[48:49], v[42:43], v[78:79], v[48:49]
	v_pk_fma_f32 v[50:51], v[42:43], v[98:99], v[50:51]
	s_waitcnt lgkmcnt(2)
	v_pk_fma_f32 v[48:49], v[36:37], v[72:73], v[48:49]
	s_lshl_b32 s35, s34, 4
	v_pk_fma_f32 v[50:51], v[36:37], v[92:93], v[50:51]
	v_pk_fma_f32 v[48:49], v[38:39], v[74:75], v[48:49]
	v_lshl_add_u32 v80, s34, 6, v158
	s_add_i32 s35, s2, s35
	v_mul_f32_e32 v45, v46, v45
	v_pk_fma_f32 v[50:51], v[38:39], v[94:95], v[50:51]
	s_waitcnt lgkmcnt(1)
	v_pk_fma_f32 v[48:49], v[32:33], v[64:65], v[48:49]
	ds_read_b32 v163, v80 offset:59648
	v_mov_b32_e32 v80, s35
	v_fmac_f32_e32 v45, v52, v47
	v_cmp_eq_u32_e32 vcc, s5, v156
	s_add_i32 s4, s4, 4
	v_pk_fma_f32 v[50:51], v[32:33], v[88:89], v[50:51]
	v_pk_fma_f32 v[48:49], v[34:35], v[66:67], v[48:49]
	ds_read_b128 v[80:83], v80 offset:60672
	v_cndmask_b32_e32 v58, v101, v45, vcc
	v_lshl_add_u32 v45, s4, 10, v157
	v_pk_fma_f32 v[50:51], v[34:35], v[90:91], v[50:51]
	s_waitcnt lgkmcnt(2)
	v_pk_fma_f32 v[48:49], v[28:29], v[60:61], v[48:49]
	v_add_u32_e32 v47, 0xa900, v45
	v_lshl_add_u32 v45, s4, 6, v158
	v_pk_fma_f32 v[50:51], v[28:29], v[84:85], v[50:51]
	v_pk_fma_f32 v[48:49], v[30:31], v[62:63], v[48:49]
	v_add_u32_e32 v46, 0xa900, v45
	v_pk_fma_f32 v[50:51], v[30:31], v[86:87], v[50:51]
	v_add_f32_e32 v45, v48, v49
	v_add_f32_e32 v48, v50, v51
	s_lshl_b32 s4, s4, 4
	v_add_f32_dpp v45, v45, v45 row_half_mirror row_mask:0xf bank_mask:0xf bound_ctrl:1
	v_add_f32_dpp v48, v48, v48 row_half_mirror row_mask:0xf bank_mask:0xf bound_ctrl:1
	s_add_i32 s4, s2, s4
	v_add_f32_dpp v45, v45, v45 quad_perm:[2,3,0,1] row_mask:0xf bank_mask:0xf bound_ctrl:1
	v_add_f32_dpp v49, v48, v48 quad_perm:[2,3,0,1] row_mask:0xf bank_mask:0xf bound_ctrl:1
	s_waitcnt lgkmcnt(0)
	v_mul_f32_e32 v48, v52, v80
	v_add_f32_dpp v45, v45, v45 quad_perm:[1,0,3,2] row_mask:0xf bank_mask:0xf bound_ctrl:1
	v_fma_f32 v45, -v48, v45, v163
	v_mov_b32_e32 v80, v83
	v_pk_mul_f32 v[44:45], v[44:45], v[80:81]
	v_cmp_eq_u32_e32 vcc, s34, v156
	v_pk_mul_f32 v[50:51], v[44:45], v[44:45] op_sel:[0,1] op_sel_hi:[0,1]
	v_add_f32_dpp v44, v49, v49 quad_perm:[1,0,3,2] row_mask:0xf bank_mask:0xf bound_ctrl:1
	v_mul_f32_e32 v45, v82, v45
	v_pk_fma_f32 v[40:41], v[76:77], v[50:51], v[40:41]
	v_pk_fma_f32 v[52:53], v[78:79], v[50:51], v[42:43]
	v_pk_fma_f32 v[36:37], v[72:73], v[50:51], v[36:37]
	v_pk_fma_f32 v[54:55], v[74:75], v[50:51], v[38:39]
	v_pk_fma_f32 v[32:33], v[64:65], v[50:51], v[32:33]
	v_pk_fma_f32 v[56:57], v[66:67], v[50:51], v[34:35]
	v_pk_fma_f32 v[28:29], v[60:61], v[50:51], v[28:29]
	v_pk_fma_f32 v[50:51], v[62:63], v[50:51], v[30:31]
	v_fmac_f32_e32 v45, v48, v44
	s_add_i32 s5, s4, 0xed00
	v_pk_mul_f32 v[42:43], v[48:49], v[40:41] op_sel_hi:[0,1]
	v_pk_mul_f32 v[40:41], v[48:49], v[52:53] op_sel_hi:[0,1]
	v_pk_mul_f32 v[38:39], v[48:49], v[36:37] op_sel_hi:[0,1]
	v_pk_mul_f32 v[36:37], v[48:49], v[54:55] op_sel_hi:[0,1]
	v_pk_mul_f32 v[34:35], v[48:49], v[32:33] op_sel_hi:[0,1]
	v_pk_mul_f32 v[32:33], v[48:49], v[56:57] op_sel_hi:[0,1]
	v_pk_mul_f32 v[30:31], v[48:49], v[28:29] op_sel_hi:[0,1]
	v_pk_mul_f32 v[28:29], v[48:49], v[50:51] op_sel_hi:[0,1]
	v_cndmask_b32_e32 v44, v58, v45, vcc
	s_and_b64 vcc, exec, s[40:41]
	s_mov_b64 s[40:41], 0
	s_mov_b32 s4, 4
	s_cbranch_vccnz .LBB0_981
	v_lshlrev_b32_e32 v46, 11, v156
	v_mov_b32_e32 v47, v3
	v_lshl_add_u64 v[46:47], v[0:1], 0, v[46:47]
	global_store_dword v[46:47], v44, off
	s_branch .LBB0_969

; #define LAS __attribute__((address_space(3)))
; __device__ __forceinline__ f32x2 fma2(f32x2 a, f32x2 b, f32x2 c) { return __builtin_elementwise_fma(a, b, c); }
; __device__ __forceinline__ float sum8(float x) { x += dppf<0x141>(x); x += dppf<0x4E>(x); x += dppf<0xB1>(x); return x; }
; __device__ __forceinline__ GOps8 g_ld8(const LAS float* B, int t, int kq, int vidx) {
;     GOps8 o; const LAS float* V = B + t * 256 + kq * 16;
; #pragma unroll
;     for (int h = 0; h < 4; ++h) { o.q[h] = *(const LAS f32x4*)(V + 4 * h); o.k[h] = *(const LAS f32x4*)(V + 128 + 4 * h); }
;     o.v = B[4096 + t * 16 + vidx]; o.sc = *(const LAS f32x4*)(B + 4352 + t * 4); return o;
; template <int TB> __device__ __forceinline__ void gdn_block8(f32x2 (&S)[8], const LAS float* B, int kq, int vidx, float* oo) {
;     ...
;     for (int t0 = 0; t0 < TB; t0 += SCAN_UNR) {
;         float P = 1.f, iP = 1.f;
; #pragma unroll
;         for (int tt = 0; tt < SCAN_UNR; ++tt) {
;             const int t = t0 + tt;
;             const GOps8 n = g_ld8(B, (t + 1) & 15, kq, vidx);
;             const f32x2 k[8] = PAIRS8(c.k), q[8] = PAIRS8(c.q);
;             f32x2 pk = S[0] * k[0], pq = S[0] * q[0];
; #pragma unroll
;             for (int e = 1; e < 8; ++e) { pk = fma2(S[e], k[e], pk); pq = fma2(S[e], q[e], pq); }
;             const float dk = sum8(pk.x + pk.y), dq = sum8(pq.x + pq.y);
;             P *= c.sc.x; iP *= c.sc.w;
;             const float coef = c.sc.y * (c.v - P * dk);
;             const float cs = coef * iP; const f32x2 cf2 = {cs, cs};
; #pragma unroll
;             for (int e = 0; e < 8; ++e) S[e] = fma2(k[e], cf2, S[e]);
;             const float o = P * dq + c.sc.z * coef;
;             okA = (kq == t) ? o : okA; okB = (kq + 8 == t) ? o : okB;
;             c = n;
;         }
;         const f32x2 p2 = {P, P};
; #pragma unroll
;         for (int e = 0; e < 8; ++e) S[e] = S[e] * p2;
;     }
.LBB0_984:
.Lgdn16_top:
	v_mov_b32_e32 v97, s48
	ds_read_b128 v[64:67], v159 offset:512
	ds_read_b128 v[48:51], v159 offset:0
	ds_read_b128 v[68:71], v159 offset:640
	ds_read_b128 v[52:55], v159 offset:128
	ds_read_b128 v[72:75], v159 offset:768
	ds_read_b128 v[56:59], v159 offset:256
	ds_read_b128 v[76:79], v159 offset:896
	ds_read_b128 v[60:63], v159 offset:384
	ds_read_b128 v[80:83], v97 offset:0
	ds_read_b32 v84, v160 offset:16384
	ds_read_b128 v[194:197], v159 offset:1536
	ds_read_b128 v[178:181], v159 offset:1024
	ds_read_b128 v[198:201], v159 offset:1664
	ds_read_b128 v[182:185], v159 offset:1152
	ds_read_b128 v[202:205], v159 offset:1792
	ds_read_b128 v[186:189], v159 offset:1280
	ds_read_b128 v[206:209], v159 offset:1920
	s_waitcnt lgkmcnt(7)
	v_pk_mul_f32 v[86:87], v[108:109], v[64:65]
	v_pk_mul_f32 v[88:89], v[108:109], v[48:49]
	v_pk_fma_f32 v[86:87], v[110:111], v[66:67], v[86:87]
	v_pk_fma_f32 v[88:89], v[110:111], v[50:51], v[88:89]
	v_pk_fma_f32 v[86:87], v[112:113], v[68:69], v[86:87]
	v_pk_fma_f32 v[88:89], v[112:113], v[52:53], v[88:89]
	v_pk_fma_f32 v[86:87], v[114:115], v[70:71], v[86:87]
	v_pk_fma_f32 v[88:89], v[114:115], v[54:55], v[88:89]
	v_pk_fma_f32 v[86:87], v[116:117], v[72:73], v[86:87]
	v_pk_fma_f32 v[88:89], v[116:117], v[56:57], v[88:89]
	v_pk_fma_f32 v[86:87], v[118:119], v[74:75], v[86:87]
	v_pk_fma_f32 v[88:89], v[118:119], v[58:59], v[88:89]
	v_pk_fma_f32 v[86:87], v[120:121], v[76:77], v[86:87]
	v_pk_fma_f32 v[88:89], v[120:121], v[60:61], v[88:89]
	v_pk_fma_f32 v[86:87], v[122:123], v[78:79], v[86:87]
	v_pk_fma_f32 v[88:89], v[122:123], v[62:63], v[88:89]
	v_add_f32_e32 v86, v86, v87
	v_add_f32_e32 v88, v88, v89
	ds_read_b128 v[190:193], v159 offset:1408
	v_add_f32_dpp v86, v86, v86 row_half_mirror row_mask:0xf bank_mask:0xf bound_ctrl:1
	v_add_f32_dpp v88, v88, v88 row_half_mirror row_mask:0xf bank_mask:0xf bound_ctrl:1
	ds_read_b128 v[210:213], v97 offset:16
	v_add_f32_dpp v86, v86, v86 quad_perm:[2,3,0,1] row_mask:0xf bank_mask:0xf bound_ctrl:1
	v_add_f32_dpp v88, v88, v88 quad_perm:[2,3,0,1] row_mask:0xf bank_mask:0xf bound_ctrl:1
	ds_read_b32 v214, v160 offset:16448
	v_add_f32_dpp v86, v86, v86 quad_perm:[1,0,3,2] row_mask:0xf bank_mask:0xf bound_ctrl:1
	v_add_f32_dpp v88, v88, v88 quad_perm:[1,0,3,2] row_mask:0xf bank_mask:0xf bound_ctrl:1
	v_fma_f32 v94, -v80, v86, v84
	v_mul_f32_e32 v95, v80, v88
	v_mul_f32_e32 v94, v81, v94
	v_cmp_eq_u32_e32 vcc, 0, v156
	v_mul_f32_e32 v92, v94, v83
	v_fma_f32 v96, v82, v94, v95
	v_pk_fma_f32 v[108:109], v[64:65], v[92:93], v[108:109] op_sel_hi:[1,0,1]
	v_pk_fma_f32 v[110:111], v[66:67], v[92:93], v[110:111] op_sel_hi:[1,0,1]
	v_cndmask_b32_e32 v37, v37, v96, vcc
	v_pk_fma_f32 v[112:113], v[68:69], v[92:93], v[112:113] op_sel_hi:[1,0,1]
	v_pk_fma_f32 v[114:115], v[70:71], v[92:93], v[114:115] op_sel_hi:[1,0,1]
	v_pk_fma_f32 v[116:117], v[72:73], v[92:93], v[116:117] op_sel_hi:[1,0,1]
	v_pk_fma_f32 v[118:119], v[74:75], v[92:93], v[118:119] op_sel_hi:[1,0,1]
	v_pk_fma_f32 v[120:121], v[76:77], v[92:93], v[120:121] op_sel_hi:[1,0,1]
	v_pk_fma_f32 v[122:123], v[78:79], v[92:93], v[122:123] op_sel_hi:[1,0,1]
	ds_read_b128 v[64:67], v159 offset:2560
	ds_read_b128 v[48:51], v159 offset:2048
	ds_read_b128 v[68:71], v159 offset:2688
	ds_read_b128 v[52:55], v159 offset:2176
	ds_read_b128 v[72:75], v159 offset:2816
	ds_read_b128 v[56:59], v159 offset:2304
	ds_read_b128 v[76:79], v159 offset:2944
	s_waitcnt lgkmcnt(7)
	v_pk_mul_f32 v[86:87], v[108:109], v[194:195]
	v_pk_mul_f32 v[88:89], v[108:109], v[178:179]
	v_pk_fma_f32 v[86:87], v[110:111], v[196:197], v[86:87]
	v_pk_fma_f32 v[88:89], v[110:111], v[180:181], v[88:89]
	v_pk_fma_f32 v[86:87], v[112:113], v[198:199], v[86:87]
	v_pk_fma_f32 v[88:89], v[112:113], v[182:183], v[88:89]
	v_mul_f32_e32 v90, v80, v210
	v_mul_f32_e32 v91, v83, v213
	v_pk_fma_f32 v[86:87], v[114:115], v[200:201], v[86:87]
	v_pk_fma_f32 v[88:89], v[114:115], v[184:185], v[88:89]
	v_pk_fma_f32 v[86:87], v[116:117], v[202:203], v[86:87]
	v_pk_fma_f32 v[88:89], v[116:117], v[186:187], v[88:89]
	v_pk_fma_f32 v[86:87], v[118:119], v[204:205], v[86:87]
	v_pk_fma_f32 v[88:89], v[118:119], v[188:189], v[88:89]
	v_pk_fma_f32 v[86:87], v[120:121], v[206:207], v[86:87]
	v_pk_fma_f32 v[88:89], v[120:121], v[190:191], v[88:89]
	v_pk_fma_f32 v[86:87], v[122:123], v[208:209], v[86:87]
	v_pk_fma_f32 v[88:89], v[122:123], v[192:193], v[88:89]
	v_add_f32_e32 v86, v86, v87
	v_add_f32_e32 v88, v88, v89
	ds_read_b128 v[60:63], v159 offset:2432
	v_add_f32_dpp v86, v86, v86 row_half_mirror row_mask:0xf bank_mask:0xf bound_ctrl:1
	v_add_f32_dpp v88, v88, v88 row_half_mirror row_mask:0xf bank_mask:0xf bound_ctrl:1
	ds_read_b128 v[80:83], v97 offset:32
	v_add_f32_dpp v86, v86, v86 quad_perm:[2,3,0,1] row_mask:0xf bank_mask:0xf bound_ctrl:1
	v_add_f32_dpp v88, v88, v88 quad_perm:[2,3,0,1] row_mask:0xf bank_mask:0xf bound_ctrl:1
	ds_read_b32 v84, v160 offset:16512
	v_add_f32_dpp v86, v86, v86 quad_perm:[1,0,3,2] row_mask:0xf bank_mask:0xf bound_ctrl:1
	v_add_f32_dpp v88, v88, v88 quad_perm:[1,0,3,2] row_mask:0xf bank_mask:0xf bound_ctrl:1
	v_fma_f32 v94, -v90, v86, v214
	v_mul_f32_e32 v95, v90, v88
	v_mul_f32_e32 v94, v211, v94
	v_cmp_eq_u32_e32 vcc, 1, v156
	v_mul_f32_e32 v92, v94, v91
	v_fma_f32 v96, v212, v94, v95
	v_pk_fma_f32 v[108:109], v[194:195], v[92:93], v[108:109] op_sel_hi:[1,0,1]
	v_pk_fma_f32 v[110:111], v[196:197], v[92:93], v[110:111] op_sel_hi:[1,0,1]
	v_cndmask_b32_e32 v37, v37, v96, vcc
	v_pk_fma_f32 v[112:113], v[198:199], v[92:93], v[112:113] op_sel_hi:[1,0,1]
	v_pk_fma_f32 v[114:115], v[200:201], v[92:93], v[114:115] op_sel_hi:[1,0,1]
	v_pk_fma_f32 v[116:117], v[202:203], v[92:93], v[116:117] op_sel_hi:[1,0,1]
	v_pk_fma_f32 v[118:119], v[204:205], v[92:93], v[118:119] op_sel_hi:[1,0,1]
	v_pk_fma_f32 v[120:121], v[206:207], v[92:93], v[120:121] op_sel_hi:[1,0,1]
	v_pk_fma_f32 v[122:123], v[208:209], v[92:93], v[122:123] op_sel_hi:[1,0,1]
	ds_read_b128 v[194:197], v159 offset:3584
	ds_read_b128 v[178:181], v159 offset:3072
	ds_read_b128 v[198:201], v159 offset:3712
	ds_read_b128 v[182:185], v159 offset:3200
	ds_read_b128 v[202:205], v159 offset:3840
	ds_read_b128 v[186:189], v159 offset:3328
	ds_read_b128 v[206:209], v159 offset:3968
	s_waitcnt lgkmcnt(7)
; #define LAS __attribute__((address_space(3)))
; __device__ __forceinline__ f32x2 fma2(f32x2 a, f32x2 b, f32x2 c) { return __builtin_elementwise_fma(a, b, c); }
; __device__ __forceinline__ float sum8(float x) { x += dppf<0x141>(x); x += dppf<0x4E>(x); x += dppf<0xB1>(x); return x; }
; __device__ __forceinline__ GOps8 g_ld8(const LAS float* B, int t, int kq, int vidx) {
;     GOps8 o; const LAS float* V = B + t * 256 + kq * 16;
; #pragma unroll
;     for (int h = 0; h < 4; ++h) { o.q[h] = *(const LAS f32x4*)(V + 4 * h); o.k[h] = *(const LAS f32x4*)(V + 128 + 4 * h); }
;     o.v = B[4096 + t * 16 + vidx]; o.sc = *(const LAS f32x4*)(B + 4352 + t * 4); return o;
; template <int TB> __device__ __forceinline__ void gdn_block8(f32x2 (&S)[8], const LAS float* B, int kq, int vidx, float* oo) {
;     ...
;     for (int t0 = 0; t0 < TB; t0 += SCAN_UNR) {
;         float P = 1.f, iP = 1.f;
; #pragma unroll
;         for (int tt = 0; tt < SCAN_UNR; ++tt) {
;             const int t = t0 + tt;
;             const GOps8 n = g_ld8(B, (t + 1) & 15, kq, vidx);
;             const f32x2 k[8] = PAIRS8(c.k), q[8] = PAIRS8(c.q);
;             f32x2 pk = S[0] * k[0], pq = S[0] * q[0];
; #pragma unroll
;             for (int e = 1; e < 8; ++e) { pk = fma2(S[e], k[e], pk); pq = fma2(S[e], q[e], pq); }
;             const float dk = sum8(pk.x + pk.y), dq = sum8(pq.x + pq.y);
;             P *= c.sc.x; iP *= c.sc.w;
;             const float coef = c.sc.y * (c.v - P * dk);
;             const float cs = coef * iP; const f32x2 cf2 = {cs, cs};
; #pragma unroll
;             for (int e = 0; e < 8; ++e) S[e] = fma2(k[e], cf2, S[e]);
;             const float o = P * dq + c.sc.z * coef;
;             okA = (kq == t) ? o : okA; okB = (kq + 8 == t) ? o : okB;
;             c = n;
;         }
;         const f32x2 p2 = {P, P};
; #pragma unroll
;         for (int e = 0; e < 8; ++e) S[e] = S[e] * p2;
;     }
	v_pk_mul_f32 v[86:87], v[108:109], v[64:65]
	v_pk_mul_f32 v[88:89], v[108:109], v[48:49]
	v_pk_fma_f32 v[86:87], v[110:111], v[66:67], v[86:87]
	v_pk_fma_f32 v[88:89], v[110:111], v[50:51], v[88:89]
	v_pk_fma_f32 v[86:87], v[112:113], v[68:69], v[86:87]
	v_pk_fma_f32 v[88:89], v[112:113], v[52:53], v[88:89]
	v_mul_f32_e32 v90, v90, v80
	v_mul_f32_e32 v91, v91, v83
	v_pk_fma_f32 v[86:87], v[114:115], v[70:71], v[86:87]
	v_pk_fma_f32 v[88:89], v[114:115], v[54:55], v[88:89]
	v_pk_fma_f32 v[86:87], v[116:117], v[72:73], v[86:87]
	v_pk_fma_f32 v[88:89], v[116:117], v[56:57], v[88:89]
	v_pk_fma_f32 v[86:87], v[118:119], v[74:75], v[86:87]
	v_pk_fma_f32 v[88:89], v[118:119], v[58:59], v[88:89]
	v_pk_fma_f32 v[86:87], v[120:121], v[76:77], v[86:87]
	v_pk_fma_f32 v[88:89], v[120:121], v[60:61], v[88:89]
	v_pk_fma_f32 v[86:87], v[122:123], v[78:79], v[86:87]
	v_pk_fma_f32 v[88:89], v[122:123], v[62:63], v[88:89]
	v_add_f32_e32 v86, v86, v87
	v_add_f32_e32 v88, v88, v89
	ds_read_b128 v[190:193], v159 offset:3456
	v_add_f32_dpp v86, v86, v86 row_half_mirror row_mask:0xf bank_mask:0xf bound_ctrl:1
	v_add_f32_dpp v88, v88, v88 row_half_mirror row_mask:0xf bank_mask:0xf bound_ctrl:1
	ds_read_b128 v[210:213], v97 offset:48
	v_add_f32_dpp v86, v86, v86 quad_perm:[2,3,0,1] row_mask:0xf bank_mask:0xf bound_ctrl:1
	v_add_f32_dpp v88, v88, v88 quad_perm:[2,3,0,1] row_mask:0xf bank_mask:0xf bound_ctrl:1
	ds_read_b32 v214, v160 offset:16576
	v_add_f32_dpp v86, v86, v86 quad_perm:[1,0,3,2] row_mask:0xf bank_mask:0xf bound_ctrl:1
	v_add_f32_dpp v88, v88, v88 quad_perm:[1,0,3,2] row_mask:0xf bank_mask:0xf bound_ctrl:1
	v_fma_f32 v94, -v90, v86, v84
	v_mul_f32_e32 v95, v90, v88
	v_mul_f32_e32 v94, v81, v94
	v_cmp_eq_u32_e32 vcc, 2, v156
	v_mul_f32_e32 v92, v94, v91
	v_fma_f32 v96, v82, v94, v95
	v_pk_fma_f32 v[108:109], v[64:65], v[92:93], v[108:109] op_sel_hi:[1,0,1]
	v_pk_fma_f32 v[110:111], v[66:67], v[92:93], v[110:111] op_sel_hi:[1,0,1]
	v_cndmask_b32_e32 v37, v37, v96, vcc
	v_pk_fma_f32 v[112:113], v[68:69], v[92:93], v[112:113] op_sel_hi:[1,0,1]
	v_pk_fma_f32 v[114:115], v[70:71], v[92:93], v[114:115] op_sel_hi:[1,0,1]
	v_pk_fma_f32 v[116:117], v[72:73], v[92:93], v[116:117] op_sel_hi:[1,0,1]
	v_pk_fma_f32 v[118:119], v[74:75], v[92:93], v[118:119] op_sel_hi:[1,0,1]
	v_pk_fma_f32 v[120:121], v[76:77], v[92:93], v[120:121] op_sel_hi:[1,0,1]
	v_pk_fma_f32 v[122:123], v[78:79], v[92:93], v[122:123] op_sel_hi:[1,0,1]
	ds_read_b128 v[64:67], v159 offset:4608
	ds_read_b128 v[48:51], v159 offset:4096
	ds_read_b128 v[68:71], v159 offset:4736
	ds_read_b128 v[52:55], v159 offset:4224
	ds_read_b128 v[72:75], v159 offset:4864
	ds_read_b128 v[56:59], v159 offset:4352
	ds_read_b128 v[76:79], v159 offset:4992
	s_waitcnt lgkmcnt(7)
	v_pk_mul_f32 v[86:87], v[108:109], v[194:195]
	v_pk_mul_f32 v[88:89], v[108:109], v[178:179]
	v_pk_fma_f32 v[86:87], v[110:111], v[196:197], v[86:87]
	v_pk_fma_f32 v[88:89], v[110:111], v[180:181], v[88:89]
	v_pk_fma_f32 v[86:87], v[112:113], v[198:199], v[86:87]
	v_pk_fma_f32 v[88:89], v[112:113], v[182:183], v[88:89]
	v_mul_f32_e32 v90, v90, v210
	v_mul_f32_e32 v91, v91, v213
	v_pk_fma_f32 v[86:87], v[114:115], v[200:201], v[86:87]
	v_pk_fma_f32 v[88:89], v[114:115], v[184:185], v[88:89]
	v_pk_fma_f32 v[86:87], v[116:117], v[202:203], v[86:87]
	v_pk_fma_f32 v[88:89], v[116:117], v[186:187], v[88:89]
	v_pk_fma_f32 v[86:87], v[118:119], v[204:205], v[86:87]
	v_pk_fma_f32 v[88:89], v[118:119], v[188:189], v[88:89]
	v_pk_fma_f32 v[86:87], v[120:121], v[206:207], v[86:87]
	v_pk_fma_f32 v[88:89], v[120:121], v[190:191], v[88:89]
	v_pk_fma_f32 v[86:87], v[122:123], v[208:209], v[86:87]
	v_pk_fma_f32 v[88:89], v[122:123], v[192:193], v[88:89]
	v_add_f32_e32 v86, v86, v87
	v_add_f32_e32 v88, v88, v89
	ds_read_b128 v[60:63], v159 offset:4480
	v_add_f32_dpp v86, v86, v86 row_half_mirror row_mask:0xf bank_mask:0xf bound_ctrl:1
	v_add_f32_dpp v88, v88, v88 row_half_mirror row_mask:0xf bank_mask:0xf bound_ctrl:1
	ds_read_b128 v[80:83], v97 offset:64
	v_add_f32_dpp v86, v86, v86 quad_perm:[2,3,0,1] row_mask:0xf bank_mask:0xf bound_ctrl:1
	v_add_f32_dpp v88, v88, v88 quad_perm:[2,3,0,1] row_mask:0xf bank_mask:0xf bound_ctrl:1
	ds_read_b32 v84, v160 offset:16640
	v_add_f32_dpp v86, v86, v86 quad_perm:[1,0,3,2] row_mask:0xf bank_mask:0xf bound_ctrl:1
	v_add_f32_dpp v88, v88, v88 quad_perm:[1,0,3,2] row_mask:0xf bank_mask:0xf bound_ctrl:1
	v_fma_f32 v94, -v90, v86, v214
	v_mul_f32_e32 v95, v90, v88
	v_mul_f32_e32 v94, v211, v94
	v_cmp_eq_u32_e32 vcc, 3, v156
	v_mul_f32_e32 v92, v94, v91
	v_fma_f32 v96, v212, v94, v95
	v_pk_fma_f32 v[108:109], v[194:195], v[92:93], v[108:109] op_sel_hi:[1,0,1]
	v_pk_fma_f32 v[110:111], v[196:197], v[92:93], v[110:111] op_sel_hi:[1,0,1]
	v_cndmask_b32_e32 v37, v37, v96, vcc
	v_pk_fma_f32 v[112:113], v[198:199], v[92:93], v[112:113] op_sel_hi:[1,0,1]
	v_pk_fma_f32 v[114:115], v[200:201], v[92:93], v[114:115] op_sel_hi:[1,0,1]
	v_pk_fma_f32 v[116:117], v[202:203], v[92:93], v[116:117] op_sel_hi:[1,0,1]
	v_pk_fma_f32 v[118:119], v[204:205], v[92:93], v[118:119] op_sel_hi:[1,0,1]
	v_pk_fma_f32 v[120:121], v[206:207], v[92:93], v[120:121] op_sel_hi:[1,0,1]
	v_pk_fma_f32 v[122:123], v[208:209], v[92:93], v[122:123] op_sel_hi:[1,0,1]
	v_pk_mul_f32 v[108:109], v[90:91], v[108:109] op_sel_hi:[0,1]
	v_pk_mul_f32 v[110:111], v[90:91], v[110:111] op_sel_hi:[0,1]
	v_pk_mul_f32 v[112:113], v[90:91], v[112:113] op_sel_hi:[0,1]
	v_pk_mul_f32 v[114:115], v[90:91], v[114:115] op_sel_hi:[0,1]
	v_pk_mul_f32 v[116:117], v[90:91], v[116:117] op_sel_hi:[0,1]
	v_pk_mul_f32 v[118:119], v[90:91], v[118:119] op_sel_hi:[0,1]
	v_pk_mul_f32 v[120:121], v[90:91], v[120:121] op_sel_hi:[0,1]
	v_pk_mul_f32 v[122:123], v[90:91], v[122:123] op_sel_hi:[0,1]
	ds_read_b128 v[194:197], v159 offset:5632
	ds_read_b128 v[178:181], v159 offset:5120
	ds_read_b128 v[198:201], v159 offset:5760
	ds_read_b128 v[182:185], v159 offset:5248
	ds_read_b128 v[202:205], v159 offset:5888
	ds_read_b128 v[186:189], v159 offset:5376
	ds_read_b128 v[206:209], v159 offset:6016
	s_waitcnt lgkmcnt(7)
; #define LAS __attribute__((address_space(3)))
; __device__ __forceinline__ f32x2 fma2(f32x2 a, f32x2 b, f32x2 c) { return __builtin_elementwise_fma(a, b, c); }
; __device__ __forceinline__ float sum8(float x) { x += dppf<0x141>(x); x += dppf<0x4E>(x); x += dppf<0xB1>(x); return x; }
; __device__ __forceinline__ GOps8 g_ld8(const LAS float* B, int t, int kq, int vidx) {
;     GOps8 o; const LAS float* V = B + t * 256 + kq * 16;
; #pragma unroll
;     for (int h = 0; h < 4; ++h) { o.q[h] = *(const LAS f32x4*)(V + 4 * h); o.k[h] = *(const LAS f32x4*)(V + 128 + 4 * h); }
;     o.v = B[4096 + t * 16 + vidx]; o.sc = *(const LAS f32x4*)(B + 4352 + t * 4); return o;
; template <int TB> __device__ __forceinline__ void gdn_block8(f32x2 (&S)[8], const LAS float* B, int kq, int vidx, float* oo) {
;     ...
;     for (int t0 = 0; t0 < TB; t0 += SCAN_UNR) {
;         float P = 1.f, iP = 1.f;
; #pragma unroll
;         for (int tt = 0; tt < SCAN_UNR; ++tt) {
;             const int t = t0 + tt;
;             const GOps8 n = g_ld8(B, (t + 1) & 15, kq, vidx);
;             const f32x2 k[8] = PAIRS8(c.k), q[8] = PAIRS8(c.q);
;             f32x2 pk = S[0] * k[0], pq = S[0] * q[0];
; #pragma unroll
;             for (int e = 1; e < 8; ++e) { pk = fma2(S[e], k[e], pk); pq = fma2(S[e], q[e], pq); }
;             const float dk = sum8(pk.x + pk.y), dq = sum8(pq.x + pq.y);
;             P *= c.sc.x; iP *= c.sc.w;
;             const float coef = c.sc.y * (c.v - P * dk);
;             const float cs = coef * iP; const f32x2 cf2 = {cs, cs};
; #pragma unroll
;             for (int e = 0; e < 8; ++e) S[e] = fma2(k[e], cf2, S[e]);
;             const float o = P * dq + c.sc.z * coef;
;             okA = (kq == t) ? o : okA; okB = (kq + 8 == t) ? o : okB;
;             c = n;
;         }
;         const f32x2 p2 = {P, P};
; #pragma unroll
;         for (int e = 0; e < 8; ++e) S[e] = S[e] * p2;
;     }
	v_pk_mul_f32 v[86:87], v[108:109], v[64:65]
	v_pk_mul_f32 v[88:89], v[108:109], v[48:49]
	v_pk_fma_f32 v[86:87], v[110:111], v[66:67], v[86:87]
	v_pk_fma_f32 v[88:89], v[110:111], v[50:51], v[88:89]
	v_pk_fma_f32 v[86:87], v[112:113], v[68:69], v[86:87]
	v_pk_fma_f32 v[88:89], v[112:113], v[52:53], v[88:89]
	v_pk_fma_f32 v[86:87], v[114:115], v[70:71], v[86:87]
	v_pk_fma_f32 v[88:89], v[114:115], v[54:55], v[88:89]
	v_pk_fma_f32 v[86:87], v[116:117], v[72:73], v[86:87]
	v_pk_fma_f32 v[88:89], v[116:117], v[56:57], v[88:89]
	v_pk_fma_f32 v[86:87], v[118:119], v[74:75], v[86:87]
	v_pk_fma_f32 v[88:89], v[118:119], v[58:59], v[88:89]
	v_pk_fma_f32 v[86:87], v[120:121], v[76:77], v[86:87]
	v_pk_fma_f32 v[88:89], v[120:121], v[60:61], v[88:89]
	v_pk_fma_f32 v[86:87], v[122:123], v[78:79], v[86:87]
	v_pk_fma_f32 v[88:89], v[122:123], v[62:63], v[88:89]
	v_add_f32_e32 v86, v86, v87
	v_add_f32_e32 v88, v88, v89
	ds_read_b128 v[190:193], v159 offset:5504
	v_add_f32_dpp v86, v86, v86 row_half_mirror row_mask:0xf bank_mask:0xf bound_ctrl:1
	v_add_f32_dpp v88, v88, v88 row_half_mirror row_mask:0xf bank_mask:0xf bound_ctrl:1
	ds_read_b128 v[210:213], v97 offset:80
	v_add_f32_dpp v86, v86, v86 quad_perm:[2,3,0,1] row_mask:0xf bank_mask:0xf bound_ctrl:1
	v_add_f32_dpp v88, v88, v88 quad_perm:[2,3,0,1] row_mask:0xf bank_mask:0xf bound_ctrl:1
	ds_read_b32 v214, v160 offset:16704
	v_add_f32_dpp v86, v86, v86 quad_perm:[1,0,3,2] row_mask:0xf bank_mask:0xf bound_ctrl:1
	v_add_f32_dpp v88, v88, v88 quad_perm:[1,0,3,2] row_mask:0xf bank_mask:0xf bound_ctrl:1
	v_fma_f32 v94, -v80, v86, v84
	v_mul_f32_e32 v95, v80, v88
	v_mul_f32_e32 v94, v81, v94
	v_cmp_eq_u32_e32 vcc, 4, v156
	v_mul_f32_e32 v92, v94, v83
	v_fma_f32 v96, v82, v94, v95
	v_pk_fma_f32 v[108:109], v[64:65], v[92:93], v[108:109] op_sel_hi:[1,0,1]
	v_pk_fma_f32 v[110:111], v[66:67], v[92:93], v[110:111] op_sel_hi:[1,0,1]
	v_cndmask_b32_e32 v37, v37, v96, vcc
	v_pk_fma_f32 v[112:113], v[68:69], v[92:93], v[112:113] op_sel_hi:[1,0,1]
	v_pk_fma_f32 v[114:115], v[70:71], v[92:93], v[114:115] op_sel_hi:[1,0,1]
	v_pk_fma_f32 v[116:117], v[72:73], v[92:93], v[116:117] op_sel_hi:[1,0,1]
	v_pk_fma_f32 v[118:119], v[74:75], v[92:93], v[118:119] op_sel_hi:[1,0,1]
	v_pk_fma_f32 v[120:121], v[76:77], v[92:93], v[120:121] op_sel_hi:[1,0,1]
	v_pk_fma_f32 v[122:123], v[78:79], v[92:93], v[122:123] op_sel_hi:[1,0,1]
	ds_read_b128 v[64:67], v159 offset:6656
	ds_read_b128 v[48:51], v159 offset:6144
	ds_read_b128 v[68:71], v159 offset:6784
	ds_read_b128 v[52:55], v159 offset:6272
	ds_read_b128 v[72:75], v159 offset:6912
	ds_read_b128 v[56:59], v159 offset:6400
	ds_read_b128 v[76:79], v159 offset:7040
	s_waitcnt lgkmcnt(7)
	v_pk_mul_f32 v[86:87], v[108:109], v[194:195]
	v_pk_mul_f32 v[88:89], v[108:109], v[178:179]
	v_pk_fma_f32 v[86:87], v[110:111], v[196:197], v[86:87]
	v_pk_fma_f32 v[88:89], v[110:111], v[180:181], v[88:89]
	v_pk_fma_f32 v[86:87], v[112:113], v[198:199], v[86:87]
	v_pk_fma_f32 v[88:89], v[112:113], v[182:183], v[88:89]
	v_mul_f32_e32 v90, v80, v210
	v_mul_f32_e32 v91, v83, v213
	v_pk_fma_f32 v[86:87], v[114:115], v[200:201], v[86:87]
	v_pk_fma_f32 v[88:89], v[114:115], v[184:185], v[88:89]
	v_pk_fma_f32 v[86:87], v[116:117], v[202:203], v[86:87]
	v_pk_fma_f32 v[88:89], v[116:117], v[186:187], v[88:89]
	v_pk_fma_f32 v[86:87], v[118:119], v[204:205], v[86:87]
	v_pk_fma_f32 v[88:89], v[118:119], v[188:189], v[88:89]
	v_pk_fma_f32 v[86:87], v[120:121], v[206:207], v[86:87]
	v_pk_fma_f32 v[88:89], v[120:121], v[190:191], v[88:89]
	v_pk_fma_f32 v[86:87], v[122:123], v[208:209], v[86:87]
	v_pk_fma_f32 v[88:89], v[122:123], v[192:193], v[88:89]
	v_add_f32_e32 v86, v86, v87
	v_add_f32_e32 v88, v88, v89
	ds_read_b128 v[60:63], v159 offset:6528
	v_add_f32_dpp v86, v86, v86 row_half_mirror row_mask:0xf bank_mask:0xf bound_ctrl:1
	v_add_f32_dpp v88, v88, v88 row_half_mirror row_mask:0xf bank_mask:0xf bound_ctrl:1
	ds_read_b128 v[80:83], v97 offset:96
	v_add_f32_dpp v86, v86, v86 quad_perm:[2,3,0,1] row_mask:0xf bank_mask:0xf bound_ctrl:1
	v_add_f32_dpp v88, v88, v88 quad_perm:[2,3,0,1] row_mask:0xf bank_mask:0xf bound_ctrl:1
	ds_read_b32 v84, v160 offset:16768
	v_add_f32_dpp v86, v86, v86 quad_perm:[1,0,3,2] row_mask:0xf bank_mask:0xf bound_ctrl:1
	v_add_f32_dpp v88, v88, v88 quad_perm:[1,0,3,2] row_mask:0xf bank_mask:0xf bound_ctrl:1
	v_fma_f32 v94, -v90, v86, v214
	v_mul_f32_e32 v95, v90, v88
	v_mul_f32_e32 v94, v211, v94
	v_cmp_eq_u32_e32 vcc, 5, v156
	v_mul_f32_e32 v92, v94, v91
	v_fma_f32 v96, v212, v94, v95
	v_pk_fma_f32 v[108:109], v[194:195], v[92:93], v[108:109] op_sel_hi:[1,0,1]
	v_pk_fma_f32 v[110:111], v[196:197], v[92:93], v[110:111] op_sel_hi:[1,0,1]
	v_cndmask_b32_e32 v37, v37, v96, vcc
	v_pk_fma_f32 v[112:113], v[198:199], v[92:93], v[112:113] op_sel_hi:[1,0,1]
	v_pk_fma_f32 v[114:115], v[200:201], v[92:93], v[114:115] op_sel_hi:[1,0,1]
	v_pk_fma_f32 v[116:117], v[202:203], v[92:93], v[116:117] op_sel_hi:[1,0,1]
	v_pk_fma_f32 v[118:119], v[204:205], v[92:93], v[118:119] op_sel_hi:[1,0,1]
	v_pk_fma_f32 v[120:121], v[206:207], v[92:93], v[120:121] op_sel_hi:[1,0,1]
	v_pk_fma_f32 v[122:123], v[208:209], v[92:93], v[122:123] op_sel_hi:[1,0,1]
	ds_read_b128 v[194:197], v159 offset:7680
	ds_read_b128 v[178:181], v159 offset:7168
	ds_read_b128 v[198:201], v159 offset:7808
	ds_read_b128 v[182:185], v159 offset:7296
	ds_read_b128 v[202:205], v159 offset:7936
	ds_read_b128 v[186:189], v159 offset:7424
	ds_read_b128 v[206:209], v159 offset:8064
	s_waitcnt lgkmcnt(7)
; #define LAS __attribute__((address_space(3)))
; __device__ __forceinline__ f32x2 fma2(f32x2 a, f32x2 b, f32x2 c) { return __builtin_elementwise_fma(a, b, c); }
; __device__ __forceinline__ float sum8(float x) { x += dppf<0x141>(x); x += dppf<0x4E>(x); x += dppf<0xB1>(x); return x; }
; __device__ __forceinline__ GOps8 g_ld8(const LAS float* B, int t, int kq, int vidx) {
;     GOps8 o; const LAS float* V = B + t * 256 + kq * 16;
; #pragma unroll
;     for (int h = 0; h < 4; ++h) { o.q[h] = *(const LAS f32x4*)(V + 4 * h); o.k[h] = *(const LAS f32x4*)(V + 128 + 4 * h); }
;     o.v = B[4096 + t * 16 + vidx]; o.sc = *(const LAS f32x4*)(B + 4352 + t * 4); return o;
; template <int TB> __device__ __forceinline__ void gdn_block8(f32x2 (&S)[8], const LAS float* B, int kq, int vidx, float* oo) {
;     ...
;     for (int t0 = 0; t0 < TB; t0 += SCAN_UNR) {
;         float P = 1.f, iP = 1.f;
; #pragma unroll
;         for (int tt = 0; tt < SCAN_UNR; ++tt) {
;             const int t = t0 + tt;
;             const GOps8 n = g_ld8(B, (t + 1) & 15, kq, vidx);
;             const f32x2 k[8] = PAIRS8(c.k), q[8] = PAIRS8(c.q);
;             f32x2 pk = S[0] * k[0], pq = S[0] * q[0];
; #pragma unroll
;             for (int e = 1; e < 8; ++e) { pk = fma2(S[e], k[e], pk); pq = fma2(S[e], q[e], pq); }
;             const float dk = sum8(pk.x + pk.y), dq = sum8(pq.x + pq.y);
;             P *= c.sc.x; iP *= c.sc.w;
;             const float coef = c.sc.y * (c.v - P * dk);
;             const float cs = coef * iP; const f32x2 cf2 = {cs, cs};
; #pragma unroll
;             for (int e = 0; e < 8; ++e) S[e] = fma2(k[e], cf2, S[e]);
;             const float o = P * dq + c.sc.z * coef;
;             okA = (kq == t) ? o : okA; okB = (kq + 8 == t) ? o : okB;
;             c = n;
;         }
;         const f32x2 p2 = {P, P};
; #pragma unroll
;         for (int e = 0; e < 8; ++e) S[e] = S[e] * p2;
;     }
	v_pk_mul_f32 v[86:87], v[108:109], v[64:65]
	v_pk_mul_f32 v[88:89], v[108:109], v[48:49]
	v_pk_fma_f32 v[86:87], v[110:111], v[66:67], v[86:87]
	v_pk_fma_f32 v[88:89], v[110:111], v[50:51], v[88:89]
	v_pk_fma_f32 v[86:87], v[112:113], v[68:69], v[86:87]
	v_pk_fma_f32 v[88:89], v[112:113], v[52:53], v[88:89]
	v_mul_f32_e32 v90, v90, v80
	v_mul_f32_e32 v91, v91, v83
	v_pk_fma_f32 v[86:87], v[114:115], v[70:71], v[86:87]
	v_pk_fma_f32 v[88:89], v[114:115], v[54:55], v[88:89]
	v_pk_fma_f32 v[86:87], v[116:117], v[72:73], v[86:87]
	v_pk_fma_f32 v[88:89], v[116:117], v[56:57], v[88:89]
	v_pk_fma_f32 v[86:87], v[118:119], v[74:75], v[86:87]
	v_pk_fma_f32 v[88:89], v[118:119], v[58:59], v[88:89]
	v_pk_fma_f32 v[86:87], v[120:121], v[76:77], v[86:87]
	v_pk_fma_f32 v[88:89], v[120:121], v[60:61], v[88:89]
	v_pk_fma_f32 v[86:87], v[122:123], v[78:79], v[86:87]
	v_pk_fma_f32 v[88:89], v[122:123], v[62:63], v[88:89]
	v_add_f32_e32 v86, v86, v87
	v_add_f32_e32 v88, v88, v89
	ds_read_b128 v[190:193], v159 offset:7552
	v_add_f32_dpp v86, v86, v86 row_half_mirror row_mask:0xf bank_mask:0xf bound_ctrl:1
	v_add_f32_dpp v88, v88, v88 row_half_mirror row_mask:0xf bank_mask:0xf bound_ctrl:1
	ds_read_b128 v[210:213], v97 offset:112
	v_add_f32_dpp v86, v86, v86 quad_perm:[2,3,0,1] row_mask:0xf bank_mask:0xf bound_ctrl:1
	v_add_f32_dpp v88, v88, v88 quad_perm:[2,3,0,1] row_mask:0xf bank_mask:0xf bound_ctrl:1
	ds_read_b32 v214, v160 offset:16832
	v_add_f32_dpp v86, v86, v86 quad_perm:[1,0,3,2] row_mask:0xf bank_mask:0xf bound_ctrl:1
	v_add_f32_dpp v88, v88, v88 quad_perm:[1,0,3,2] row_mask:0xf bank_mask:0xf bound_ctrl:1
	v_fma_f32 v94, -v90, v86, v84
	v_mul_f32_e32 v95, v90, v88
	v_mul_f32_e32 v94, v81, v94
	v_cmp_eq_u32_e32 vcc, 6, v156
	v_mul_f32_e32 v92, v94, v91
	v_fma_f32 v96, v82, v94, v95
	v_pk_fma_f32 v[108:109], v[64:65], v[92:93], v[108:109] op_sel_hi:[1,0,1]
	v_pk_fma_f32 v[110:111], v[66:67], v[92:93], v[110:111] op_sel_hi:[1,0,1]
	v_cndmask_b32_e32 v37, v37, v96, vcc
	v_pk_fma_f32 v[112:113], v[68:69], v[92:93], v[112:113] op_sel_hi:[1,0,1]
	v_pk_fma_f32 v[114:115], v[70:71], v[92:93], v[114:115] op_sel_hi:[1,0,1]
	v_pk_fma_f32 v[116:117], v[72:73], v[92:93], v[116:117] op_sel_hi:[1,0,1]
	v_pk_fma_f32 v[118:119], v[74:75], v[92:93], v[118:119] op_sel_hi:[1,0,1]
	v_pk_fma_f32 v[120:121], v[76:77], v[92:93], v[120:121] op_sel_hi:[1,0,1]
	v_pk_fma_f32 v[122:123], v[78:79], v[92:93], v[122:123] op_sel_hi:[1,0,1]
	ds_read_b128 v[64:67], v159 offset:8704
	ds_read_b128 v[48:51], v159 offset:8192
	ds_read_b128 v[68:71], v159 offset:8832
	ds_read_b128 v[52:55], v159 offset:8320
	ds_read_b128 v[72:75], v159 offset:8960
	ds_read_b128 v[56:59], v159 offset:8448
	ds_read_b128 v[76:79], v159 offset:9088
	s_waitcnt lgkmcnt(7)
	v_pk_mul_f32 v[86:87], v[108:109], v[194:195]
	v_pk_mul_f32 v[88:89], v[108:109], v[178:179]
	v_pk_fma_f32 v[86:87], v[110:111], v[196:197], v[86:87]
	v_pk_fma_f32 v[88:89], v[110:111], v[180:181], v[88:89]
	v_pk_fma_f32 v[86:87], v[112:113], v[198:199], v[86:87]
	v_pk_fma_f32 v[88:89], v[112:113], v[182:183], v[88:89]
	v_mul_f32_e32 v90, v90, v210
	v_mul_f32_e32 v91, v91, v213
	v_pk_fma_f32 v[86:87], v[114:115], v[200:201], v[86:87]
	v_pk_fma_f32 v[88:89], v[114:115], v[184:185], v[88:89]
	v_pk_fma_f32 v[86:87], v[116:117], v[202:203], v[86:87]
	v_pk_fma_f32 v[88:89], v[116:117], v[186:187], v[88:89]
	v_pk_fma_f32 v[86:87], v[118:119], v[204:205], v[86:87]
	v_pk_fma_f32 v[88:89], v[118:119], v[188:189], v[88:89]
	v_pk_fma_f32 v[86:87], v[120:121], v[206:207], v[86:87]
	v_pk_fma_f32 v[88:89], v[120:121], v[190:191], v[88:89]
	v_pk_fma_f32 v[86:87], v[122:123], v[208:209], v[86:87]
	v_pk_fma_f32 v[88:89], v[122:123], v[192:193], v[88:89]
	v_add_f32_e32 v86, v86, v87
	v_add_f32_e32 v88, v88, v89
	ds_read_b128 v[60:63], v159 offset:8576
	v_add_f32_dpp v86, v86, v86 row_half_mirror row_mask:0xf bank_mask:0xf bound_ctrl:1
	v_add_f32_dpp v88, v88, v88 row_half_mirror row_mask:0xf bank_mask:0xf bound_ctrl:1
	ds_read_b128 v[80:83], v97 offset:128
	v_add_f32_dpp v86, v86, v86 quad_perm:[2,3,0,1] row_mask:0xf bank_mask:0xf bound_ctrl:1
	v_add_f32_dpp v88, v88, v88 quad_perm:[2,3,0,1] row_mask:0xf bank_mask:0xf bound_ctrl:1
	ds_read_b32 v84, v160 offset:16896
	v_add_f32_dpp v86, v86, v86 quad_perm:[1,0,3,2] row_mask:0xf bank_mask:0xf bound_ctrl:1
	v_add_f32_dpp v88, v88, v88 quad_perm:[1,0,3,2] row_mask:0xf bank_mask:0xf bound_ctrl:1
	v_fma_f32 v94, -v90, v86, v214
	v_mul_f32_e32 v95, v90, v88
	v_mul_f32_e32 v94, v211, v94
	v_cmp_eq_u32_e32 vcc, 7, v156
	v_mul_f32_e32 v92, v94, v91
	v_fma_f32 v96, v212, v94, v95
	v_pk_fma_f32 v[108:109], v[194:195], v[92:93], v[108:109] op_sel_hi:[1,0,1]
	v_pk_fma_f32 v[110:111], v[196:197], v[92:93], v[110:111] op_sel_hi:[1,0,1]
	v_cndmask_b32_e32 v37, v37, v96, vcc
	v_pk_fma_f32 v[112:113], v[198:199], v[92:93], v[112:113] op_sel_hi:[1,0,1]
	v_pk_fma_f32 v[114:115], v[200:201], v[92:93], v[114:115] op_sel_hi:[1,0,1]
	v_pk_fma_f32 v[116:117], v[202:203], v[92:93], v[116:117] op_sel_hi:[1,0,1]
	v_pk_fma_f32 v[118:119], v[204:205], v[92:93], v[118:119] op_sel_hi:[1,0,1]
	v_pk_fma_f32 v[120:121], v[206:207], v[92:93], v[120:121] op_sel_hi:[1,0,1]
	v_pk_fma_f32 v[122:123], v[208:209], v[92:93], v[122:123] op_sel_hi:[1,0,1]
	v_pk_mul_f32 v[108:109], v[90:91], v[108:109] op_sel_hi:[0,1]
	v_pk_mul_f32 v[110:111], v[90:91], v[110:111] op_sel_hi:[0,1]
	v_pk_mul_f32 v[112:113], v[90:91], v[112:113] op_sel_hi:[0,1]
	v_pk_mul_f32 v[114:115], v[90:91], v[114:115] op_sel_hi:[0,1]
	v_pk_mul_f32 v[116:117], v[90:91], v[116:117] op_sel_hi:[0,1]
	v_pk_mul_f32 v[118:119], v[90:91], v[118:119] op_sel_hi:[0,1]
	v_pk_mul_f32 v[120:121], v[90:91], v[120:121] op_sel_hi:[0,1]
	v_pk_mul_f32 v[122:123], v[90:91], v[122:123] op_sel_hi:[0,1]
	ds_read_b128 v[194:197], v159 offset:9728
	ds_read_b128 v[178:181], v159 offset:9216
	ds_read_b128 v[198:201], v159 offset:9856
	ds_read_b128 v[182:185], v159 offset:9344
	ds_read_b128 v[202:205], v159 offset:9984
	ds_read_b128 v[186:189], v159 offset:9472
	ds_read_b128 v[206:209], v159 offset:10112
	s_waitcnt lgkmcnt(7)
; #define LAS __attribute__((address_space(3)))
; __device__ __forceinline__ f32x2 fma2(f32x2 a, f32x2 b, f32x2 c) { return __builtin_elementwise_fma(a, b, c); }
; __device__ __forceinline__ float sum8(float x) { x += dppf<0x141>(x); x += dppf<0x4E>(x); x += dppf<0xB1>(x); return x; }
; __device__ __forceinline__ GOps8 g_ld8(const LAS float* B, int t, int kq, int vidx) {
;     GOps8 o; const LAS float* V = B + t * 256 + kq * 16;
; #pragma unroll
;     for (int h = 0; h < 4; ++h) { o.q[h] = *(const LAS f32x4*)(V + 4 * h); o.k[h] = *(const LAS f32x4*)(V + 128 + 4 * h); }
;     o.v = B[4096 + t * 16 + vidx]; o.sc = *(const LAS f32x4*)(B + 4352 + t * 4); return o;
; template <int TB> __device__ __forceinline__ void gdn_block8(f32x2 (&S)[8], const LAS float* B, int kq, int vidx, float* oo) {
;     ...
;     for (int t0 = 0; t0 < TB; t0 += SCAN_UNR) {
;         float P = 1.f, iP = 1.f;
; #pragma unroll
;         for (int tt = 0; tt < SCAN_UNR; ++tt) {
;             const int t = t0 + tt;
;             const GOps8 n = g_ld8(B, (t + 1) & 15, kq, vidx);
;             const f32x2 k[8] = PAIRS8(c.k), q[8] = PAIRS8(c.q);
;             f32x2 pk = S[0] * k[0], pq = S[0] * q[0];
; #pragma unroll
;             for (int e = 1; e < 8; ++e) { pk = fma2(S[e], k[e], pk); pq = fma2(S[e], q[e], pq); }
;             const float dk = sum8(pk.x + pk.y), dq = sum8(pq.x + pq.y);
;             P *= c.sc.x; iP *= c.sc.w;
;             const float coef = c.sc.y * (c.v - P * dk);
;             const float cs = coef * iP; const f32x2 cf2 = {cs, cs};
; #pragma unroll
;             for (int e = 0; e < 8; ++e) S[e] = fma2(k[e], cf2, S[e]);
;             const float o = P * dq + c.sc.z * coef;
;             okA = (kq == t) ? o : okA; okB = (kq + 8 == t) ? o : okB;
;             c = n;
;         }
;         const f32x2 p2 = {P, P};
; #pragma unroll
;         for (int e = 0; e < 8; ++e) S[e] = S[e] * p2;
;     }
	v_pk_mul_f32 v[86:87], v[108:109], v[64:65]
	v_pk_mul_f32 v[88:89], v[108:109], v[48:49]
	v_pk_fma_f32 v[86:87], v[110:111], v[66:67], v[86:87]
	v_pk_fma_f32 v[88:89], v[110:111], v[50:51], v[88:89]
	v_pk_fma_f32 v[86:87], v[112:113], v[68:69], v[86:87]
	v_pk_fma_f32 v[88:89], v[112:113], v[52:53], v[88:89]
	v_pk_fma_f32 v[86:87], v[114:115], v[70:71], v[86:87]
	v_pk_fma_f32 v[88:89], v[114:115], v[54:55], v[88:89]
	v_pk_fma_f32 v[86:87], v[116:117], v[72:73], v[86:87]
	v_pk_fma_f32 v[88:89], v[116:117], v[56:57], v[88:89]
	v_pk_fma_f32 v[86:87], v[118:119], v[74:75], v[86:87]
	v_pk_fma_f32 v[88:89], v[118:119], v[58:59], v[88:89]
	v_pk_fma_f32 v[86:87], v[120:121], v[76:77], v[86:87]
	v_pk_fma_f32 v[88:89], v[120:121], v[60:61], v[88:89]
	v_pk_fma_f32 v[86:87], v[122:123], v[78:79], v[86:87]
	v_pk_fma_f32 v[88:89], v[122:123], v[62:63], v[88:89]
	v_add_f32_e32 v86, v86, v87
	v_add_f32_e32 v88, v88, v89
	ds_read_b128 v[190:193], v159 offset:9600
	v_add_f32_dpp v86, v86, v86 row_half_mirror row_mask:0xf bank_mask:0xf bound_ctrl:1
	v_add_f32_dpp v88, v88, v88 row_half_mirror row_mask:0xf bank_mask:0xf bound_ctrl:1
	ds_read_b128 v[210:213], v97 offset:144
	v_add_f32_dpp v86, v86, v86 quad_perm:[2,3,0,1] row_mask:0xf bank_mask:0xf bound_ctrl:1
	v_add_f32_dpp v88, v88, v88 quad_perm:[2,3,0,1] row_mask:0xf bank_mask:0xf bound_ctrl:1
	ds_read_b32 v214, v160 offset:16960
	v_add_f32_dpp v86, v86, v86 quad_perm:[1,0,3,2] row_mask:0xf bank_mask:0xf bound_ctrl:1
	v_add_f32_dpp v88, v88, v88 quad_perm:[1,0,3,2] row_mask:0xf bank_mask:0xf bound_ctrl:1
	v_fma_f32 v94, -v80, v86, v84
	v_mul_f32_e32 v95, v80, v88
	v_mul_f32_e32 v94, v81, v94
	v_cmp_eq_u32_e32 vcc, 0, v156
	v_mul_f32_e32 v92, v94, v83
	v_fma_f32 v96, v82, v94, v95
	v_pk_fma_f32 v[108:109], v[64:65], v[92:93], v[108:109] op_sel_hi:[1,0,1]
	v_pk_fma_f32 v[110:111], v[66:67], v[92:93], v[110:111] op_sel_hi:[1,0,1]
	v_cndmask_b32_e32 v36, v36, v96, vcc
	v_pk_fma_f32 v[112:113], v[68:69], v[92:93], v[112:113] op_sel_hi:[1,0,1]
	v_pk_fma_f32 v[114:115], v[70:71], v[92:93], v[114:115] op_sel_hi:[1,0,1]
	v_pk_fma_f32 v[116:117], v[72:73], v[92:93], v[116:117] op_sel_hi:[1,0,1]
	v_pk_fma_f32 v[118:119], v[74:75], v[92:93], v[118:119] op_sel_hi:[1,0,1]
	v_pk_fma_f32 v[120:121], v[76:77], v[92:93], v[120:121] op_sel_hi:[1,0,1]
	v_pk_fma_f32 v[122:123], v[78:79], v[92:93], v[122:123] op_sel_hi:[1,0,1]
	ds_read_b128 v[64:67], v159 offset:10752
	ds_read_b128 v[48:51], v159 offset:10240
	ds_read_b128 v[68:71], v159 offset:10880
	ds_read_b128 v[52:55], v159 offset:10368
	ds_read_b128 v[72:75], v159 offset:11008
	ds_read_b128 v[56:59], v159 offset:10496
	ds_read_b128 v[76:79], v159 offset:11136
	s_waitcnt lgkmcnt(7)
	v_pk_mul_f32 v[86:87], v[108:109], v[194:195]
	v_pk_mul_f32 v[88:89], v[108:109], v[178:179]
	v_pk_fma_f32 v[86:87], v[110:111], v[196:197], v[86:87]
	v_pk_fma_f32 v[88:89], v[110:111], v[180:181], v[88:89]
	v_pk_fma_f32 v[86:87], v[112:113], v[198:199], v[86:87]
	v_pk_fma_f32 v[88:89], v[112:113], v[182:183], v[88:89]
	v_mul_f32_e32 v90, v80, v210
	v_mul_f32_e32 v91, v83, v213
	v_pk_fma_f32 v[86:87], v[114:115], v[200:201], v[86:87]
	v_pk_fma_f32 v[88:89], v[114:115], v[184:185], v[88:89]
	v_pk_fma_f32 v[86:87], v[116:117], v[202:203], v[86:87]
	v_pk_fma_f32 v[88:89], v[116:117], v[186:187], v[88:89]
	v_pk_fma_f32 v[86:87], v[118:119], v[204:205], v[86:87]
	v_pk_fma_f32 v[88:89], v[118:119], v[188:189], v[88:89]
	v_pk_fma_f32 v[86:87], v[120:121], v[206:207], v[86:87]
	v_pk_fma_f32 v[88:89], v[120:121], v[190:191], v[88:89]
	v_pk_fma_f32 v[86:87], v[122:123], v[208:209], v[86:87]
	v_pk_fma_f32 v[88:89], v[122:123], v[192:193], v[88:89]
	v_add_f32_e32 v86, v86, v87
	v_add_f32_e32 v88, v88, v89
	ds_read_b128 v[60:63], v159 offset:10624
	v_add_f32_dpp v86, v86, v86 row_half_mirror row_mask:0xf bank_mask:0xf bound_ctrl:1
	v_add_f32_dpp v88, v88, v88 row_half_mirror row_mask:0xf bank_mask:0xf bound_ctrl:1
	ds_read_b128 v[80:83], v97 offset:160
	v_add_f32_dpp v86, v86, v86 quad_perm:[2,3,0,1] row_mask:0xf bank_mask:0xf bound_ctrl:1
	v_add_f32_dpp v88, v88, v88 quad_perm:[2,3,0,1] row_mask:0xf bank_mask:0xf bound_ctrl:1
	ds_read_b32 v84, v160 offset:17024
	v_add_f32_dpp v86, v86, v86 quad_perm:[1,0,3,2] row_mask:0xf bank_mask:0xf bound_ctrl:1
	v_add_f32_dpp v88, v88, v88 quad_perm:[1,0,3,2] row_mask:0xf bank_mask:0xf bound_ctrl:1
	v_fma_f32 v94, -v90, v86, v214
	v_mul_f32_e32 v95, v90, v88
	v_mul_f32_e32 v94, v211, v94
	v_cmp_eq_u32_e32 vcc, 1, v156
	v_mul_f32_e32 v92, v94, v91
	v_fma_f32 v96, v212, v94, v95
	v_pk_fma_f32 v[108:109], v[194:195], v[92:93], v[108:109] op_sel_hi:[1,0,1]
	v_pk_fma_f32 v[110:111], v[196:197], v[92:93], v[110:111] op_sel_hi:[1,0,1]
	v_cndmask_b32_e32 v36, v36, v96, vcc
	v_pk_fma_f32 v[112:113], v[198:199], v[92:93], v[112:113] op_sel_hi:[1,0,1]
	v_pk_fma_f32 v[114:115], v[200:201], v[92:93], v[114:115] op_sel_hi:[1,0,1]
	v_pk_fma_f32 v[116:117], v[202:203], v[92:93], v[116:117] op_sel_hi:[1,0,1]
	v_pk_fma_f32 v[118:119], v[204:205], v[92:93], v[118:119] op_sel_hi:[1,0,1]
	v_pk_fma_f32 v[120:121], v[206:207], v[92:93], v[120:121] op_sel_hi:[1,0,1]
	v_pk_fma_f32 v[122:123], v[208:209], v[92:93], v[122:123] op_sel_hi:[1,0,1]
	ds_read_b128 v[194:197], v159 offset:11776
	ds_read_b128 v[178:181], v159 offset:11264
	ds_read_b128 v[198:201], v159 offset:11904
	ds_read_b128 v[182:185], v159 offset:11392
	ds_read_b128 v[202:205], v159 offset:12032
	ds_read_b128 v[186:189], v159 offset:11520
	ds_read_b128 v[206:209], v159 offset:12160
	s_waitcnt lgkmcnt(7)
; #define LAS __attribute__((address_space(3)))
; __device__ __forceinline__ f32x2 fma2(f32x2 a, f32x2 b, f32x2 c) { return __builtin_elementwise_fma(a, b, c); }
; __device__ __forceinline__ float sum8(float x) { x += dppf<0x141>(x); x += dppf<0x4E>(x); x += dppf<0xB1>(x); return x; }
; __device__ __forceinline__ GOps8 g_ld8(const LAS float* B, int t, int kq, int vidx) {
;     GOps8 o; const LAS float* V = B + t * 256 + kq * 16;
; #pragma unroll
;     for (int h = 0; h < 4; ++h) { o.q[h] = *(const LAS f32x4*)(V + 4 * h); o.k[h] = *(const LAS f32x4*)(V + 128 + 4 * h); }
;     o.v = B[4096 + t * 16 + vidx]; o.sc = *(const LAS f32x4*)(B + 4352 + t * 4); return o;
; template <int TB> __device__ __forceinline__ void gdn_block8(f32x2 (&S)[8], const LAS float* B, int kq, int vidx, float* oo) {
;     ...
;     for (int t0 = 0; t0 < TB; t0 += SCAN_UNR) {
;         float P = 1.f, iP = 1.f;
; #pragma unroll
;         for (int tt = 0; tt < SCAN_UNR; ++tt) {
;             const int t = t0 + tt;
;             const GOps8 n = g_ld8(B, (t + 1) & 15, kq, vidx);
;             const f32x2 k[8] = PAIRS8(c.k), q[8] = PAIRS8(c.q);
;             f32x2 pk = S[0] * k[0], pq = S[0] * q[0];
; #pragma unroll
;             for (int e = 1; e < 8; ++e) { pk = fma2(S[e], k[e], pk); pq = fma2(S[e], q[e], pq); }
;             const float dk = sum8(pk.x + pk.y), dq = sum8(pq.x + pq.y);
;             P *= c.sc.x; iP *= c.sc.w;
;             const float coef = c.sc.y * (c.v - P * dk);
;             const float cs = coef * iP; const f32x2 cf2 = {cs, cs};
; #pragma unroll
;             for (int e = 0; e < 8; ++e) S[e] = fma2(k[e], cf2, S[e]);
;             const float o = P * dq + c.sc.z * coef;
;             okA = (kq == t) ? o : okA; okB = (kq + 8 == t) ? o : okB;
;             c = n;
;         }
;         const f32x2 p2 = {P, P};
; #pragma unroll
;         for (int e = 0; e < 8; ++e) S[e] = S[e] * p2;
;     }
	v_pk_mul_f32 v[86:87], v[108:109], v[64:65]
	v_pk_mul_f32 v[88:89], v[108:109], v[48:49]
	v_pk_fma_f32 v[86:87], v[110:111], v[66:67], v[86:87]
	v_pk_fma_f32 v[88:89], v[110:111], v[50:51], v[88:89]
	v_pk_fma_f32 v[86:87], v[112:113], v[68:69], v[86:87]
	v_pk_fma_f32 v[88:89], v[112:113], v[52:53], v[88:89]
	v_mul_f32_e32 v90, v90, v80
	v_mul_f32_e32 v91, v91, v83
	v_pk_fma_f32 v[86:87], v[114:115], v[70:71], v[86:87]
	v_pk_fma_f32 v[88:89], v[114:115], v[54:55], v[88:89]
	v_pk_fma_f32 v[86:87], v[116:117], v[72:73], v[86:87]
	v_pk_fma_f32 v[88:89], v[116:117], v[56:57], v[88:89]
	v_pk_fma_f32 v[86:87], v[118:119], v[74:75], v[86:87]
	v_pk_fma_f32 v[88:89], v[118:119], v[58:59], v[88:89]
	v_pk_fma_f32 v[86:87], v[120:121], v[76:77], v[86:87]
	v_pk_fma_f32 v[88:89], v[120:121], v[60:61], v[88:89]
	v_pk_fma_f32 v[86:87], v[122:123], v[78:79], v[86:87]
	v_pk_fma_f32 v[88:89], v[122:123], v[62:63], v[88:89]
	v_add_f32_e32 v86, v86, v87
	v_add_f32_e32 v88, v88, v89
	ds_read_b128 v[190:193], v159 offset:11648
	v_add_f32_dpp v86, v86, v86 row_half_mirror row_mask:0xf bank_mask:0xf bound_ctrl:1
	v_add_f32_dpp v88, v88, v88 row_half_mirror row_mask:0xf bank_mask:0xf bound_ctrl:1
	ds_read_b128 v[210:213], v97 offset:176
	v_add_f32_dpp v86, v86, v86 quad_perm:[2,3,0,1] row_mask:0xf bank_mask:0xf bound_ctrl:1
	v_add_f32_dpp v88, v88, v88 quad_perm:[2,3,0,1] row_mask:0xf bank_mask:0xf bound_ctrl:1
	ds_read_b32 v214, v160 offset:17088
	v_add_f32_dpp v86, v86, v86 quad_perm:[1,0,3,2] row_mask:0xf bank_mask:0xf bound_ctrl:1
	v_add_f32_dpp v88, v88, v88 quad_perm:[1,0,3,2] row_mask:0xf bank_mask:0xf bound_ctrl:1
	v_fma_f32 v94, -v90, v86, v84
	v_mul_f32_e32 v95, v90, v88
	v_mul_f32_e32 v94, v81, v94
	v_cmp_eq_u32_e32 vcc, 2, v156
	v_mul_f32_e32 v92, v94, v91
	v_fma_f32 v96, v82, v94, v95
	v_pk_fma_f32 v[108:109], v[64:65], v[92:93], v[108:109] op_sel_hi:[1,0,1]
	v_pk_fma_f32 v[110:111], v[66:67], v[92:93], v[110:111] op_sel_hi:[1,0,1]
	v_cndmask_b32_e32 v36, v36, v96, vcc
	v_pk_fma_f32 v[112:113], v[68:69], v[92:93], v[112:113] op_sel_hi:[1,0,1]
	v_pk_fma_f32 v[114:115], v[70:71], v[92:93], v[114:115] op_sel_hi:[1,0,1]
	v_pk_fma_f32 v[116:117], v[72:73], v[92:93], v[116:117] op_sel_hi:[1,0,1]
	v_pk_fma_f32 v[118:119], v[74:75], v[92:93], v[118:119] op_sel_hi:[1,0,1]
	v_pk_fma_f32 v[120:121], v[76:77], v[92:93], v[120:121] op_sel_hi:[1,0,1]
	v_pk_fma_f32 v[122:123], v[78:79], v[92:93], v[122:123] op_sel_hi:[1,0,1]
	ds_read_b128 v[64:67], v159 offset:12800
	ds_read_b128 v[48:51], v159 offset:12288
	ds_read_b128 v[68:71], v159 offset:12928
	ds_read_b128 v[52:55], v159 offset:12416
	ds_read_b128 v[72:75], v159 offset:13056
	ds_read_b128 v[56:59], v159 offset:12544
	ds_read_b128 v[76:79], v159 offset:13184
	s_waitcnt lgkmcnt(7)
	v_pk_mul_f32 v[86:87], v[108:109], v[194:195]
	v_pk_mul_f32 v[88:89], v[108:109], v[178:179]
	v_pk_fma_f32 v[86:87], v[110:111], v[196:197], v[86:87]
	v_pk_fma_f32 v[88:89], v[110:111], v[180:181], v[88:89]
	v_pk_fma_f32 v[86:87], v[112:113], v[198:199], v[86:87]
	v_pk_fma_f32 v[88:89], v[112:113], v[182:183], v[88:89]
	v_mul_f32_e32 v90, v90, v210
	v_mul_f32_e32 v91, v91, v213
	v_pk_fma_f32 v[86:87], v[114:115], v[200:201], v[86:87]
	v_pk_fma_f32 v[88:89], v[114:115], v[184:185], v[88:89]
	v_pk_fma_f32 v[86:87], v[116:117], v[202:203], v[86:87]
	v_pk_fma_f32 v[88:89], v[116:117], v[186:187], v[88:89]
	v_pk_fma_f32 v[86:87], v[118:119], v[204:205], v[86:87]
	v_pk_fma_f32 v[88:89], v[118:119], v[188:189], v[88:89]
	v_pk_fma_f32 v[86:87], v[120:121], v[206:207], v[86:87]
	v_pk_fma_f32 v[88:89], v[120:121], v[190:191], v[88:89]
	v_pk_fma_f32 v[86:87], v[122:123], v[208:209], v[86:87]
	v_pk_fma_f32 v[88:89], v[122:123], v[192:193], v[88:89]
	v_add_f32_e32 v86, v86, v87
	v_add_f32_e32 v88, v88, v89
	ds_read_b128 v[60:63], v159 offset:12672
	v_add_f32_dpp v86, v86, v86 row_half_mirror row_mask:0xf bank_mask:0xf bound_ctrl:1
	v_add_f32_dpp v88, v88, v88 row_half_mirror row_mask:0xf bank_mask:0xf bound_ctrl:1
	ds_read_b128 v[80:83], v97 offset:192
	v_add_f32_dpp v86, v86, v86 quad_perm:[2,3,0,1] row_mask:0xf bank_mask:0xf bound_ctrl:1
	v_add_f32_dpp v88, v88, v88 quad_perm:[2,3,0,1] row_mask:0xf bank_mask:0xf bound_ctrl:1
	ds_read_b32 v84, v160 offset:17152
	v_add_f32_dpp v86, v86, v86 quad_perm:[1,0,3,2] row_mask:0xf bank_mask:0xf bound_ctrl:1
	v_add_f32_dpp v88, v88, v88 quad_perm:[1,0,3,2] row_mask:0xf bank_mask:0xf bound_ctrl:1
	v_fma_f32 v94, -v90, v86, v214
	v_mul_f32_e32 v95, v90, v88
	v_mul_f32_e32 v94, v211, v94
	v_cmp_eq_u32_e32 vcc, 3, v156
	v_mul_f32_e32 v92, v94, v91
	v_fma_f32 v96, v212, v94, v95
	v_pk_fma_f32 v[108:109], v[194:195], v[92:93], v[108:109] op_sel_hi:[1,0,1]
	v_pk_fma_f32 v[110:111], v[196:197], v[92:93], v[110:111] op_sel_hi:[1,0,1]
	v_cndmask_b32_e32 v36, v36, v96, vcc
	v_pk_fma_f32 v[112:113], v[198:199], v[92:93], v[112:113] op_sel_hi:[1,0,1]
	v_pk_fma_f32 v[114:115], v[200:201], v[92:93], v[114:115] op_sel_hi:[1,0,1]
	v_pk_fma_f32 v[116:117], v[202:203], v[92:93], v[116:117] op_sel_hi:[1,0,1]
	v_pk_fma_f32 v[118:119], v[204:205], v[92:93], v[118:119] op_sel_hi:[1,0,1]
	v_pk_fma_f32 v[120:121], v[206:207], v[92:93], v[120:121] op_sel_hi:[1,0,1]
	v_pk_fma_f32 v[122:123], v[208:209], v[92:93], v[122:123] op_sel_hi:[1,0,1]
	v_pk_mul_f32 v[108:109], v[90:91], v[108:109] op_sel_hi:[0,1]
	v_pk_mul_f32 v[110:111], v[90:91], v[110:111] op_sel_hi:[0,1]
	v_pk_mul_f32 v[112:113], v[90:91], v[112:113] op_sel_hi:[0,1]
	v_pk_mul_f32 v[114:115], v[90:91], v[114:115] op_sel_hi:[0,1]
	v_pk_mul_f32 v[116:117], v[90:91], v[116:117] op_sel_hi:[0,1]
	v_pk_mul_f32 v[118:119], v[90:91], v[118:119] op_sel_hi:[0,1]
	v_pk_mul_f32 v[120:121], v[90:91], v[120:121] op_sel_hi:[0,1]
	v_pk_mul_f32 v[122:123], v[90:91], v[122:123] op_sel_hi:[0,1]
	ds_read_b128 v[194:197], v159 offset:13824
	ds_read_b128 v[178:181], v159 offset:13312
	ds_read_b128 v[198:201], v159 offset:13952
	ds_read_b128 v[182:185], v159 offset:13440
	ds_read_b128 v[202:205], v159 offset:14080
	ds_read_b128 v[186:189], v159 offset:13568
	ds_read_b128 v[206:209], v159 offset:14208
	s_waitcnt lgkmcnt(7)
; #define LAS __attribute__((address_space(3)))
; __device__ __forceinline__ f32x2 fma2(f32x2 a, f32x2 b, f32x2 c) { return __builtin_elementwise_fma(a, b, c); }
; __device__ __forceinline__ float sum8(float x) { x += dppf<0x141>(x); x += dppf<0x4E>(x); x += dppf<0xB1>(x); return x; }
; __device__ __forceinline__ GOps8 g_ld8(const LAS float* B, int t, int kq, int vidx) {
;     GOps8 o; const LAS float* V = B + t * 256 + kq * 16;
; #pragma unroll
;     for (int h = 0; h < 4; ++h) { o.q[h] = *(const LAS f32x4*)(V + 4 * h); o.k[h] = *(const LAS f32x4*)(V + 128 + 4 * h); }
;     o.v = B[4096 + t * 16 + vidx]; o.sc = *(const LAS f32x4*)(B + 4352 + t * 4); return o;
; template <int TB> __device__ __forceinline__ void gdn_block8(f32x2 (&S)[8], const LAS float* B, int kq, int vidx, float* oo) {
;     ...
;     for (int t0 = 0; t0 < TB; t0 += SCAN_UNR) {
;         float P = 1.f, iP = 1.f;
; #pragma unroll
;         for (int tt = 0; tt < SCAN_UNR; ++tt) {
;             const int t = t0 + tt;
;             const GOps8 n = g_ld8(B, (t + 1) & 15, kq, vidx);
;             const f32x2 k[8] = PAIRS8(c.k), q[8] = PAIRS8(c.q);
;             f32x2 pk = S[0] * k[0], pq = S[0] * q[0];
; #pragma unroll
;             for (int e = 1; e < 8; ++e) { pk = fma2(S[e], k[e], pk); pq = fma2(S[e], q[e], pq); }
;             const float dk = sum8(pk.x + pk.y), dq = sum8(pq.x + pq.y);
;             P *= c.sc.x; iP *= c.sc.w;
;             const float coef = c.sc.y * (c.v - P * dk);
;             const float cs = coef * iP; const f32x2 cf2 = {cs, cs};
; #pragma unroll
;             for (int e = 0; e < 8; ++e) S[e] = fma2(k[e], cf2, S[e]);
;             const float o = P * dq + c.sc.z * coef;
;             okA = (kq == t) ? o : okA; okB = (kq + 8 == t) ? o : okB;
;             c = n;
;         }
;         const f32x2 p2 = {P, P};
; #pragma unroll
;         for (int e = 0; e < 8; ++e) S[e] = S[e] * p2;
;     }
	v_pk_mul_f32 v[86:87], v[108:109], v[64:65]
	v_pk_mul_f32 v[88:89], v[108:109], v[48:49]
	v_pk_fma_f32 v[86:87], v[110:111], v[66:67], v[86:87]
	v_pk_fma_f32 v[88:89], v[110:111], v[50:51], v[88:89]
	v_pk_fma_f32 v[86:87], v[112:113], v[68:69], v[86:87]
	v_pk_fma_f32 v[88:89], v[112:113], v[52:53], v[88:89]
	v_pk_fma_f32 v[86:87], v[114:115], v[70:71], v[86:87]
	v_pk_fma_f32 v[88:89], v[114:115], v[54:55], v[88:89]
	v_pk_fma_f32 v[86:87], v[116:117], v[72:73], v[86:87]
	v_pk_fma_f32 v[88:89], v[116:117], v[56:57], v[88:89]
	v_pk_fma_f32 v[86:87], v[118:119], v[74:75], v[86:87]
	v_pk_fma_f32 v[88:89], v[118:119], v[58:59], v[88:89]
	v_pk_fma_f32 v[86:87], v[120:121], v[76:77], v[86:87]
	v_pk_fma_f32 v[88:89], v[120:121], v[60:61], v[88:89]
	v_pk_fma_f32 v[86:87], v[122:123], v[78:79], v[86:87]
	v_pk_fma_f32 v[88:89], v[122:123], v[62:63], v[88:89]
	v_add_f32_e32 v86, v86, v87
	v_add_f32_e32 v88, v88, v89
	ds_read_b128 v[190:193], v159 offset:13696
	v_add_f32_dpp v86, v86, v86 row_half_mirror row_mask:0xf bank_mask:0xf bound_ctrl:1
	v_add_f32_dpp v88, v88, v88 row_half_mirror row_mask:0xf bank_mask:0xf bound_ctrl:1
	ds_read_b128 v[210:213], v97 offset:208
	v_add_f32_dpp v86, v86, v86 quad_perm:[2,3,0,1] row_mask:0xf bank_mask:0xf bound_ctrl:1
	v_add_f32_dpp v88, v88, v88 quad_perm:[2,3,0,1] row_mask:0xf bank_mask:0xf bound_ctrl:1
	ds_read_b32 v214, v160 offset:17216
	v_add_f32_dpp v86, v86, v86 quad_perm:[1,0,3,2] row_mask:0xf bank_mask:0xf bound_ctrl:1
	v_add_f32_dpp v88, v88, v88 quad_perm:[1,0,3,2] row_mask:0xf bank_mask:0xf bound_ctrl:1
	v_fma_f32 v94, -v80, v86, v84
	v_mul_f32_e32 v95, v80, v88
	v_mul_f32_e32 v94, v81, v94
	v_cmp_eq_u32_e32 vcc, 4, v156
	v_mul_f32_e32 v92, v94, v83
	v_fma_f32 v96, v82, v94, v95
	v_pk_fma_f32 v[108:109], v[64:65], v[92:93], v[108:109] op_sel_hi:[1,0,1]
	v_pk_fma_f32 v[110:111], v[66:67], v[92:93], v[110:111] op_sel_hi:[1,0,1]
	v_cndmask_b32_e32 v36, v36, v96, vcc
	v_pk_fma_f32 v[112:113], v[68:69], v[92:93], v[112:113] op_sel_hi:[1,0,1]
	v_pk_fma_f32 v[114:115], v[70:71], v[92:93], v[114:115] op_sel_hi:[1,0,1]
	v_pk_fma_f32 v[116:117], v[72:73], v[92:93], v[116:117] op_sel_hi:[1,0,1]
	v_pk_fma_f32 v[118:119], v[74:75], v[92:93], v[118:119] op_sel_hi:[1,0,1]
	v_pk_fma_f32 v[120:121], v[76:77], v[92:93], v[120:121] op_sel_hi:[1,0,1]
	v_pk_fma_f32 v[122:123], v[78:79], v[92:93], v[122:123] op_sel_hi:[1,0,1]
	ds_read_b128 v[64:67], v159 offset:14848
	ds_read_b128 v[48:51], v159 offset:14336
	ds_read_b128 v[68:71], v159 offset:14976
	ds_read_b128 v[52:55], v159 offset:14464
	ds_read_b128 v[72:75], v159 offset:15104
	ds_read_b128 v[56:59], v159 offset:14592
	ds_read_b128 v[76:79], v159 offset:15232
	s_waitcnt lgkmcnt(7)
	v_pk_mul_f32 v[86:87], v[108:109], v[194:195]
	v_pk_mul_f32 v[88:89], v[108:109], v[178:179]
	v_pk_fma_f32 v[86:87], v[110:111], v[196:197], v[86:87]
	v_pk_fma_f32 v[88:89], v[110:111], v[180:181], v[88:89]
	v_pk_fma_f32 v[86:87], v[112:113], v[198:199], v[86:87]
	v_pk_fma_f32 v[88:89], v[112:113], v[182:183], v[88:89]
	v_mul_f32_e32 v90, v80, v210
	v_mul_f32_e32 v91, v83, v213
	v_pk_fma_f32 v[86:87], v[114:115], v[200:201], v[86:87]
	v_pk_fma_f32 v[88:89], v[114:115], v[184:185], v[88:89]
	v_pk_fma_f32 v[86:87], v[116:117], v[202:203], v[86:87]
	v_pk_fma_f32 v[88:89], v[116:117], v[186:187], v[88:89]
	v_pk_fma_f32 v[86:87], v[118:119], v[204:205], v[86:87]
	v_pk_fma_f32 v[88:89], v[118:119], v[188:189], v[88:89]
	v_pk_fma_f32 v[86:87], v[120:121], v[206:207], v[86:87]
	v_pk_fma_f32 v[88:89], v[120:121], v[190:191], v[88:89]
	v_pk_fma_f32 v[86:87], v[122:123], v[208:209], v[86:87]
	v_pk_fma_f32 v[88:89], v[122:123], v[192:193], v[88:89]
	v_add_f32_e32 v86, v86, v87
	v_add_f32_e32 v88, v88, v89
	ds_read_b128 v[60:63], v159 offset:14720
	v_add_f32_dpp v86, v86, v86 row_half_mirror row_mask:0xf bank_mask:0xf bound_ctrl:1
	v_add_f32_dpp v88, v88, v88 row_half_mirror row_mask:0xf bank_mask:0xf bound_ctrl:1
	ds_read_b128 v[80:83], v97 offset:224
	v_add_f32_dpp v86, v86, v86 quad_perm:[2,3,0,1] row_mask:0xf bank_mask:0xf bound_ctrl:1
	v_add_f32_dpp v88, v88, v88 quad_perm:[2,3,0,1] row_mask:0xf bank_mask:0xf bound_ctrl:1
	ds_read_b32 v84, v160 offset:17280
	v_add_f32_dpp v86, v86, v86 quad_perm:[1,0,3,2] row_mask:0xf bank_mask:0xf bound_ctrl:1
	v_add_f32_dpp v88, v88, v88 quad_perm:[1,0,3,2] row_mask:0xf bank_mask:0xf bound_ctrl:1
	v_fma_f32 v94, -v90, v86, v214
	v_mul_f32_e32 v95, v90, v88
	v_mul_f32_e32 v94, v211, v94
	v_cmp_eq_u32_e32 vcc, 5, v156
	v_mul_f32_e32 v92, v94, v91
	v_fma_f32 v96, v212, v94, v95
	v_pk_fma_f32 v[108:109], v[194:195], v[92:93], v[108:109] op_sel_hi:[1,0,1]
	v_pk_fma_f32 v[110:111], v[196:197], v[92:93], v[110:111] op_sel_hi:[1,0,1]
	v_cndmask_b32_e32 v36, v36, v96, vcc
	v_pk_fma_f32 v[112:113], v[198:199], v[92:93], v[112:113] op_sel_hi:[1,0,1]
	v_pk_fma_f32 v[114:115], v[200:201], v[92:93], v[114:115] op_sel_hi:[1,0,1]
	v_pk_fma_f32 v[116:117], v[202:203], v[92:93], v[116:117] op_sel_hi:[1,0,1]
	v_pk_fma_f32 v[118:119], v[204:205], v[92:93], v[118:119] op_sel_hi:[1,0,1]
	v_pk_fma_f32 v[120:121], v[206:207], v[92:93], v[120:121] op_sel_hi:[1,0,1]
	v_pk_fma_f32 v[122:123], v[208:209], v[92:93], v[122:123] op_sel_hi:[1,0,1]
	ds_read_b128 v[194:197], v159 offset:15872
	ds_read_b128 v[178:181], v159 offset:15360
	ds_read_b128 v[198:201], v159 offset:16000
	ds_read_b128 v[182:185], v159 offset:15488
	ds_read_b128 v[202:205], v159 offset:16128
	ds_read_b128 v[186:189], v159 offset:15616
	ds_read_b128 v[206:209], v159 offset:16256
	s_waitcnt lgkmcnt(7)
; template <int TB> __device__ __forceinline__ void gdn_block8(f32x2 (&S)[8], const LAS float* B, int kq, int vidx, float* oo) {
;     ...
;     for (int t0 = 0; t0 < TB; t0 += SCAN_UNR) {
;         float P = 1.f, iP = 1.f;
; #pragma unroll
;         for (int tt = 0; tt < SCAN_UNR; ++tt) {
;             const int t = t0 + tt;
;             const GOps8 n = g_ld8(B, (t + 1) & 15, kq, vidx);
;             const f32x2 k[8] = PAIRS8(c.k), q[8] = PAIRS8(c.q);
;             f32x2 pk = S[0] * k[0], pq = S[0] * q[0];
; #pragma unroll
;             for (int e = 1; e < 8; ++e) { pk = fma2(S[e], k[e], pk); pq = fma2(S[e], q[e], pq); }
;             const float dk = sum8(pk.x + pk.y), dq = sum8(pq.x + pq.y);
;             P *= c.sc.x; iP *= c.sc.w;
;             const float coef = c.sc.y * (c.v - P * dk);
;             const float cs = coef * iP; const f32x2 cf2 = {cs, cs};
; #pragma unroll
;             for (int e = 0; e < 8; ++e) S[e] = fma2(k[e], cf2, S[e]);
;             const float o = P * dq + c.sc.z * coef;
;             okA = (kq == t) ? o : okA; okB = (kq + 8 == t) ? o : okB;
;             c = n;
;         }
;         const f32x2 p2 = {P, P};
; #pragma unroll
;         for (int e = 0; e < 8; ++e) S[e] = S[e] * p2;
;     }
; __device__ __forceinline__ void phase_scan(Ctx& C, int i) {
;     ...
;         for (int blk = 0; blk < SC_NBLK; ++blk) {
;             RELAUNDER;
;             G_DESC(blk, m0, tb, head, cgp, b, isprompt)
;             const bool last = isprompt ? (blk == 127) : true;
;             if (blk + 1 < SC_NBLK) G_STAGE_LOAD(blk + 1);
;             const LAS float* B = buf0 + (blk & 1) * GBUF;
;             const int col = cgp * 16 + w * 8 + sub;
;             float* oo = ORAW + m0 * GW + head * 128 + col;
;             if (cw) {
;             if (tb == 16) gdn_block8<16>(S, B, kq, w * 8 + sub, oo); else gdn_block8<8>(S, B, kq, w * 8 + sub, oo);
;             if (last) {
;                 float* So = (isprompt ? C.out + O_GDN_P + ((size_t)(i * NB + b) * GH + head) * 16384 : C.out + O_GDN_S + ((size_t)(i * SB + b) * GH + head) * 16384) + col;
; #pragma unroll
;                 for (int e = 0; e < 8; ++e) { So[(size_t)(kq * 16 + 2 * e) * 128] = S[e].x; So[(size_t)(kq * 16 + 2 * e + 1) * 128] = S[e].y; S[e] = (f32x2){Snext[2 * e], Snext[2 * e + 1]}; }
;             }
;             }
;             if (blk + 1 < SC_NBLK) G_STAGE_WRITE(blk + 1);
	v_pk_mul_f32 v[86:87], v[108:109], v[64:65]
	v_pk_mul_f32 v[88:89], v[108:109], v[48:49]
	v_pk_fma_f32 v[86:87], v[110:111], v[66:67], v[86:87]
	v_pk_fma_f32 v[88:89], v[110:111], v[50:51], v[88:89]
	v_pk_fma_f32 v[86:87], v[112:113], v[68:69], v[86:87]
	v_pk_fma_f32 v[88:89], v[112:113], v[52:53], v[88:89]
	v_mul_f32_e32 v90, v90, v80
	v_mul_f32_e32 v91, v91, v83
	v_pk_fma_f32 v[86:87], v[114:115], v[70:71], v[86:87]
	v_pk_fma_f32 v[88:89], v[114:115], v[54:55], v[88:89]
	v_pk_fma_f32 v[86:87], v[116:117], v[72:73], v[86:87]
	v_pk_fma_f32 v[88:89], v[116:117], v[56:57], v[88:89]
	v_pk_fma_f32 v[86:87], v[118:119], v[74:75], v[86:87]
	v_pk_fma_f32 v[88:89], v[118:119], v[58:59], v[88:89]
	v_pk_fma_f32 v[86:87], v[120:121], v[76:77], v[86:87]
	v_pk_fma_f32 v[88:89], v[120:121], v[60:61], v[88:89]
	v_pk_fma_f32 v[86:87], v[122:123], v[78:79], v[86:87]
	v_pk_fma_f32 v[88:89], v[122:123], v[62:63], v[88:89]
	v_add_f32_e32 v86, v86, v87
	v_add_f32_e32 v88, v88, v89
	ds_read_b128 v[190:193], v159 offset:15744
	v_add_f32_dpp v86, v86, v86 row_half_mirror row_mask:0xf bank_mask:0xf bound_ctrl:1
	v_add_f32_dpp v88, v88, v88 row_half_mirror row_mask:0xf bank_mask:0xf bound_ctrl:1
	ds_read_b128 v[210:213], v97 offset:240
	v_add_f32_dpp v86, v86, v86 quad_perm:[2,3,0,1] row_mask:0xf bank_mask:0xf bound_ctrl:1
	v_add_f32_dpp v88, v88, v88 quad_perm:[2,3,0,1] row_mask:0xf bank_mask:0xf bound_ctrl:1
	ds_read_b32 v214, v160 offset:17344
	v_add_f32_dpp v86, v86, v86 quad_perm:[1,0,3,2] row_mask:0xf bank_mask:0xf bound_ctrl:1
	v_add_f32_dpp v88, v88, v88 quad_perm:[1,0,3,2] row_mask:0xf bank_mask:0xf bound_ctrl:1
	v_fma_f32 v94, -v90, v86, v84
	v_mul_f32_e32 v95, v90, v88
	v_mul_f32_e32 v94, v81, v94
	v_cmp_eq_u32_e32 vcc, 6, v156
	v_mul_f32_e32 v92, v94, v91
	v_fma_f32 v96, v82, v94, v95
	v_pk_fma_f32 v[108:109], v[64:65], v[92:93], v[108:109] op_sel_hi:[1,0,1]
	v_pk_fma_f32 v[110:111], v[66:67], v[92:93], v[110:111] op_sel_hi:[1,0,1]
	v_cndmask_b32_e32 v36, v36, v96, vcc
	v_pk_fma_f32 v[112:113], v[68:69], v[92:93], v[112:113] op_sel_hi:[1,0,1]
	v_pk_fma_f32 v[114:115], v[70:71], v[92:93], v[114:115] op_sel_hi:[1,0,1]
	v_pk_fma_f32 v[116:117], v[72:73], v[92:93], v[116:117] op_sel_hi:[1,0,1]
	v_pk_fma_f32 v[118:119], v[74:75], v[92:93], v[118:119] op_sel_hi:[1,0,1]
	v_pk_fma_f32 v[120:121], v[76:77], v[92:93], v[120:121] op_sel_hi:[1,0,1]
	v_pk_fma_f32 v[122:123], v[78:79], v[92:93], v[122:123] op_sel_hi:[1,0,1]
	s_waitcnt lgkmcnt(0)
	v_pk_mul_f32 v[86:87], v[108:109], v[194:195]
	v_pk_mul_f32 v[88:89], v[108:109], v[178:179]
	v_pk_fma_f32 v[86:87], v[110:111], v[196:197], v[86:87]
	v_pk_fma_f32 v[88:89], v[110:111], v[180:181], v[88:89]
	v_pk_fma_f32 v[86:87], v[112:113], v[198:199], v[86:87]
	v_pk_fma_f32 v[88:89], v[112:113], v[182:183], v[88:89]
	v_mul_f32_e32 v90, v90, v210
	v_mul_f32_e32 v91, v91, v213
	v_pk_fma_f32 v[86:87], v[114:115], v[200:201], v[86:87]
	v_pk_fma_f32 v[88:89], v[114:115], v[184:185], v[88:89]
	v_pk_fma_f32 v[86:87], v[116:117], v[202:203], v[86:87]
	v_pk_fma_f32 v[88:89], v[116:117], v[186:187], v[88:89]
	v_pk_fma_f32 v[86:87], v[118:119], v[204:205], v[86:87]
	v_pk_fma_f32 v[88:89], v[118:119], v[188:189], v[88:89]
	v_pk_fma_f32 v[86:87], v[120:121], v[206:207], v[86:87]
	v_pk_fma_f32 v[88:89], v[120:121], v[190:191], v[88:89]
	v_pk_fma_f32 v[86:87], v[122:123], v[208:209], v[86:87]
	v_pk_fma_f32 v[88:89], v[122:123], v[192:193], v[88:89]
	v_add_f32_e32 v86, v86, v87
	v_add_f32_e32 v88, v88, v89
	s_nop 0
	v_add_f32_dpp v86, v86, v86 row_half_mirror row_mask:0xf bank_mask:0xf bound_ctrl:1
	v_add_f32_dpp v88, v88, v88 row_half_mirror row_mask:0xf bank_mask:0xf bound_ctrl:1
	s_nop 0
	v_add_f32_dpp v86, v86, v86 quad_perm:[2,3,0,1] row_mask:0xf bank_mask:0xf bound_ctrl:1
	v_add_f32_dpp v88, v88, v88 quad_perm:[2,3,0,1] row_mask:0xf bank_mask:0xf bound_ctrl:1
	s_nop 0
	v_add_f32_dpp v86, v86, v86 quad_perm:[1,0,3,2] row_mask:0xf bank_mask:0xf bound_ctrl:1
	v_add_f32_dpp v88, v88, v88 quad_perm:[1,0,3,2] row_mask:0xf bank_mask:0xf bound_ctrl:1
	v_fma_f32 v94, -v90, v86, v214
	v_mul_f32_e32 v95, v90, v88
	v_mul_f32_e32 v94, v211, v94
	v_cmp_eq_u32_e32 vcc, 7, v156
	v_mul_f32_e32 v92, v94, v91
	v_fma_f32 v96, v212, v94, v95
	v_pk_fma_f32 v[108:109], v[194:195], v[92:93], v[108:109] op_sel_hi:[1,0,1]
	v_pk_fma_f32 v[110:111], v[196:197], v[92:93], v[110:111] op_sel_hi:[1,0,1]
	v_cndmask_b32_e32 v36, v36, v96, vcc
	v_pk_fma_f32 v[112:113], v[198:199], v[92:93], v[112:113] op_sel_hi:[1,0,1]
	v_pk_fma_f32 v[114:115], v[200:201], v[92:93], v[114:115] op_sel_hi:[1,0,1]
	v_pk_fma_f32 v[116:117], v[202:203], v[92:93], v[116:117] op_sel_hi:[1,0,1]
	v_pk_fma_f32 v[118:119], v[204:205], v[92:93], v[118:119] op_sel_hi:[1,0,1]
	v_pk_fma_f32 v[120:121], v[206:207], v[92:93], v[120:121] op_sel_hi:[1,0,1]
	v_pk_fma_f32 v[122:123], v[208:209], v[92:93], v[122:123] op_sel_hi:[1,0,1]
	v_pk_mul_f32 v[108:109], v[90:91], v[108:109] op_sel_hi:[0,1]
	v_pk_mul_f32 v[110:111], v[90:91], v[110:111] op_sel_hi:[0,1]
	v_pk_mul_f32 v[112:113], v[90:91], v[112:113] op_sel_hi:[0,1]
	v_pk_mul_f32 v[114:115], v[90:91], v[114:115] op_sel_hi:[0,1]
	v_pk_mul_f32 v[116:117], v[90:91], v[116:117] op_sel_hi:[0,1]
	v_pk_mul_f32 v[118:119], v[90:91], v[118:119] op_sel_hi:[0,1]
	v_pk_mul_f32 v[120:121], v[90:91], v[120:121] op_sel_hi:[0,1]
	v_pk_mul_f32 v[122:123], v[90:91], v[122:123] op_sel_hi:[0,1]
	s_cmpk_gt_u32 s29, 0x7e
	s_cbranch_scc1 .Lgdn16_exit
	v_lshlrev_b32_e32 v28, 11, v156
	v_mov_b32_e32 v29, v3
	v_lshl_add_u64 v[30:31], v[0:1], 0, v[28:29]
	global_store_dword v[30:31], v37, off
	s_mov_b32 s4, 0x4000
	s_mov_b32 s5, 0
	v_lshl_add_u64 v[30:31], v[30:31], 0, s[4:5]
	global_store_dword v[30:31], v36, off
	s_mov_b32 s4, 0x8000
	v_lshl_add_u64 v[0:1], v[0:1], 0, s[4:5]
	s_add_i32 s29, s29, 1
	s_xor_b32 s2, s2, 0x4500
	v_add_u32_e32 v157, s2, v162
	s_lshl_b32 s4, s59, 2
	s_add_i32 s4, s2, s4
	v_lshl_add_u32 v158, v161, 2, s4
	v_add_u32_e32 v159, 0xa900, v157
	v_add_u32_e32 v160, 0xa900, v158
	s_add_i32 s48, s2, 0xed00
	v_mov_b32_e32 v37, 0
	v_mov_b32_e32 v36, 0
	s_waitcnt lgkmcnt(0)
	s_barrier
	s_branch .Lgdn16_top
